# P9: hoisted pool halo loads + sample-stream CUs skip prompt strips; batched WGU weight conversion; SwiGLU hand epilogue; fast div; single acc zeroing
# speedup vs baseline: 1.0505x; 1.0505x over previous
;     __device__ __forceinline__ bool next(int i, Unit& u) const { u.kb = 0; u.nk = 0; return static_tile(i, nM, nN, G, c, u.pm, u.pn); }
; template <class Epi, class Sched>
; __device__ __forceinline__ void gemm_phase(PG8_LAS unsigned char* lds, const Gemm g, const Sched& S, const Epi& E) {
;     ...
;         const bool has_next = S.next(ui + 1, nxt);
;         const char* nA = has_next ? PG8_TA(nxt) : cA; const char* nB = has_next ? PG8_TB(nxt) : cB;
; __device__ __forceinline__ void acc_zero(f32x4 (&acc)[2][2][4][2]) {
; #pragma unroll
;     for (int a = 0; a < 2; ++a)
; #pragma unroll
;         for (int b = 0; b < 2; ++b)
; #pragma unroll
;             for (int m = 0; m < 4; ++m)
; #pragma unroll
;                 for (int n = 0; n < 2; ++n) acc[a][b][m][n] = (f32x4){0.f, 0.f, 0.f, 0.f};
; }
.LBB0_185:
	s_ashr_i32 s35, s34, 31
	s_lshl_b64 s[38:39], s[34:35], 19
	s_add_u32 s38, s86, s38
	s_addc_u32 s39, s87, s39
	s_and_b64 vcc, exec, s[2:3]
	s_cbranch_vccnz .LBB0_188
	s_and_b64 s[40:41], s[40:41], exec
	s_cselect_b32 s7, s39, s9
	s_cselect_b32 s35, s38, s8
	s_add_u32 s8, s8, 0x40080
	s_addc_u32 s9, s9, 0
	s_add_u32 s40, s10, 0x100
	v_mov_b32_e32 v0, 0
	s_addc_u32 s41, s11, 0
	s_mov_b32 s10, 0
	v_mov_b32_e32 v1, v0
	v_mov_b32_e32 v2, v0
	v_mov_b32_e32 v3, v0
	v_mov_b32_e32 v4, v0
	v_mov_b32_e32 v5, v0
	v_mov_b32_e32 v6, v0
	v_mov_b32_e32 v7, v0
	v_mov_b32_e32 v16, v0
	v_mov_b32_e32 v17, v0
	v_mov_b32_e32 v18, v0
	v_mov_b32_e32 v19, v0
	v_mov_b32_e32 v20, v0
	v_mov_b32_e32 v21, v0
	v_mov_b32_e32 v22, v0
	v_mov_b32_e32 v23, v0
	v_mov_b32_e32 v32, v0
	v_mov_b32_e32 v33, v0
	v_mov_b32_e32 v34, v0
	v_mov_b32_e32 v35, v0
	v_mov_b32_e32 v36, v0
	v_mov_b32_e32 v37, v0
	v_mov_b32_e32 v38, v0
	v_mov_b32_e32 v39, v0
	v_mov_b32_e32 v48, v0
	v_mov_b32_e32 v49, v0
	v_mov_b32_e32 v50, v0
	v_mov_b32_e32 v51, v0
	v_mov_b32_e32 v52, v0
	v_mov_b32_e32 v53, v0
	v_mov_b32_e32 v54, v0
	v_mov_b32_e32 v55, v0
	v_mov_b32_e32 v8, v0
	v_mov_b32_e32 v9, v0
	v_mov_b32_e32 v10, v0
	v_mov_b32_e32 v11, v0
	v_mov_b32_e32 v12, v0
	v_mov_b32_e32 v13, v0
	v_mov_b32_e32 v14, v0
	v_mov_b32_e32 v15, v0
	v_mov_b32_e32 v24, v0
	v_mov_b32_e32 v25, v0
	v_mov_b32_e32 v26, v0
	v_mov_b32_e32 v27, v0
	v_mov_b32_e32 v28, v0
	v_mov_b32_e32 v29, v0
	v_mov_b32_e32 v30, v0
	v_mov_b32_e32 v31, v0
	v_mov_b32_e32 v40, v0
	v_mov_b32_e32 v41, v0
	v_mov_b32_e32 v42, v0
	v_mov_b32_e32 v43, v0
	v_mov_b32_e32 v44, v0
	v_mov_b32_e32 v45, v0
	v_mov_b32_e32 v46, v0
	v_mov_b32_e32 v47, v0
	v_mov_b32_e32 v56, v0
	v_mov_b32_e32 v57, v0
	v_mov_b32_e32 v58, v0
	v_mov_b32_e32 v59, v0
	v_mov_b32_e32 v60, v0
	v_mov_b32_e32 v61, v0
	v_mov_b32_e32 v62, v0
	v_mov_b32_e32 v63, v0
	v_mov_b32_e32 v64, v0
	v_mov_b32_e32 v65, v0
	v_mov_b32_e32 v66, v0
	v_mov_b32_e32 v67, v0
	v_mov_b32_e32 v68, v0
	v_mov_b32_e32 v69, v0
	v_mov_b32_e32 v70, v0
	v_mov_b32_e32 v71, v0
	v_mov_b32_e32 v80, v0
	v_mov_b32_e32 v81, v0
	v_mov_b32_e32 v82, v0
	v_mov_b32_e32 v83, v0
	v_mov_b32_e32 v84, v0
	v_mov_b32_e32 v85, v0
	v_mov_b32_e32 v86, v0
	v_mov_b32_e32 v87, v0
	v_mov_b32_e32 v96, v0
	v_mov_b32_e32 v97, v0
	v_mov_b32_e32 v98, v0
	v_mov_b32_e32 v99, v0
	v_mov_b32_e32 v100, v0
	v_mov_b32_e32 v101, v0
	v_mov_b32_e32 v102, v0
	v_mov_b32_e32 v103, v0
	v_mov_b32_e32 v112, v0
	v_mov_b32_e32 v113, v0
	v_mov_b32_e32 v114, v0
	v_mov_b32_e32 v115, v0
	v_mov_b32_e32 v116, v0
	v_mov_b32_e32 v117, v0
	v_mov_b32_e32 v118, v0
	v_mov_b32_e32 v119, v0
	v_mov_b32_e32 v72, v0
	v_mov_b32_e32 v73, v0
	v_mov_b32_e32 v74, v0
	v_mov_b32_e32 v75, v0
	v_mov_b32_e32 v76, v0
	v_mov_b32_e32 v77, v0
	v_mov_b32_e32 v78, v0
	v_mov_b32_e32 v79, v0
	v_mov_b32_e32 v88, v0
	v_mov_b32_e32 v89, v0
	v_mov_b32_e32 v90, v0
	v_mov_b32_e32 v91, v0
	v_mov_b32_e32 v92, v0
	v_mov_b32_e32 v93, v0
	v_mov_b32_e32 v94, v0
	v_mov_b32_e32 v95, v0
	v_mov_b32_e32 v104, v0
	v_mov_b32_e32 v105, v0
	v_mov_b32_e32 v106, v0
	v_mov_b32_e32 v107, v0
	v_mov_b32_e32 v108, v0
	v_mov_b32_e32 v109, v0
	v_mov_b32_e32 v110, v0
	v_mov_b32_e32 v111, v0
	v_mov_b32_e32 v120, v0
	v_mov_b32_e32 v121, v0
	v_mov_b32_e32 v122, v0
	v_mov_b32_e32 v123, v0
	v_mov_b32_e32 v124, v0
	v_mov_b32_e32 v125, v0
	v_mov_b32_e32 v126, v0
	v_mov_b32_e32 v127, v0

;     __device__ __forceinline__ bool next(int i, Unit& u) const { u.kb = 0; u.nk = 0; return static_tile(i, nM, nN, G, c, u.pm, u.pn); }
; template <class Epi, class Sched>
; __device__ __forceinline__ void gemm_phase(PG8_LAS unsigned char* lds, const Gemm g, const Sched& S, const Epi& E) {
;     ...
;         const bool has_next = S.next(ui + 1, nxt);
;         const char* nA = has_next ? PG8_TA(nxt) : cA; const char* nB = has_next ? PG8_TB(nxt) : cB;
; __device__ __forceinline__ void acc_zero(f32x4 (&acc)[2][2][4][2]) {
; #pragma unroll
;     for (int a = 0; a < 2; ++a)
; #pragma unroll
;         for (int b = 0; b < 2; ++b)
; #pragma unroll
;             for (int m = 0; m < 4; ++m)
; #pragma unroll
;                 for (int n = 0; n < 2; ++n) acc[a][b][m][n] = (f32x4){0.f, 0.f, 0.f, 0.f};
; }
.LBB0_554:
	s_ashr_i32 s35, s34, 31
	s_lshl_b64 s[38:39], s[30:31], 8
	s_lshl_b64 s[64:65], s[34:35], 18
	s_add_u32 s31, s4, s64
	s_addc_u32 s35, s5, s65
	s_add_u32 s38, s31, s38
	s_addc_u32 s39, s35, s39
	s_andn2_b64 vcc, exec, s[24:25]
	s_cbranch_vccnz .LBB0_557
	s_and_b64 s[0:1], s[0:1], exec
	s_cselect_b32 s31, s39, s45
	s_cselect_b32 s35, s38, s44
	s_add_u32 s0, s44, 0x20080
	s_addc_u32 s1, s45, 0
	s_add_u32 s44, s42, 0x100
	v_mov_b32_e32 v0, 0
	s_addc_u32 s45, s43, 0
	s_mov_b32 s42, 0
	v_mov_b32_e32 v1, v0
	v_mov_b32_e32 v2, v0
	v_mov_b32_e32 v3, v0
	v_mov_b32_e32 v8, v0
	v_mov_b32_e32 v9, v0
	v_mov_b32_e32 v10, v0
	v_mov_b32_e32 v11, v0
	v_mov_b32_e32 v28, v0
	v_mov_b32_e32 v29, v0
	v_mov_b32_e32 v30, v0
	v_mov_b32_e32 v31, v0
	v_mov_b32_e32 v48, v0
	v_mov_b32_e32 v49, v0
	v_mov_b32_e32 v50, v0
	v_mov_b32_e32 v51, v0
	v_mov_b32_e32 v56, v0
	v_mov_b32_e32 v57, v0
	v_mov_b32_e32 v58, v0
	v_mov_b32_e32 v59, v0
	v_mov_b32_e32 v64, v0
	v_mov_b32_e32 v65, v0
	v_mov_b32_e32 v66, v0
	v_mov_b32_e32 v67, v0
	v_mov_b32_e32 v72, v0
	v_mov_b32_e32 v73, v0
	v_mov_b32_e32 v74, v0
	v_mov_b32_e32 v75, v0
	v_mov_b32_e32 v80, v0
	v_mov_b32_e32 v81, v0
	v_mov_b32_e32 v82, v0
	v_mov_b32_e32 v83, v0
	v_mov_b32_e32 v4, v0
	v_mov_b32_e32 v5, v0
	v_mov_b32_e32 v6, v0
	v_mov_b32_e32 v7, v0
	v_mov_b32_e32 v12, v0
	v_mov_b32_e32 v13, v0
	v_mov_b32_e32 v14, v0
	v_mov_b32_e32 v15, v0
	v_mov_b32_e32 v32, v0
	v_mov_b32_e32 v33, v0
	v_mov_b32_e32 v34, v0
	v_mov_b32_e32 v35, v0
	v_mov_b32_e32 v52, v0
	v_mov_b32_e32 v53, v0
	v_mov_b32_e32 v54, v0
	v_mov_b32_e32 v55, v0
	v_mov_b32_e32 v60, v0
	v_mov_b32_e32 v61, v0
	v_mov_b32_e32 v62, v0
	v_mov_b32_e32 v63, v0
	v_mov_b32_e32 v68, v0
	v_mov_b32_e32 v69, v0
	v_mov_b32_e32 v70, v0
	v_mov_b32_e32 v71, v0
	v_mov_b32_e32 v76, v0
	v_mov_b32_e32 v77, v0
	v_mov_b32_e32 v78, v0
	v_mov_b32_e32 v79, v0
	v_mov_b32_e32 v84, v0
	v_mov_b32_e32 v85, v0
	v_mov_b32_e32 v86, v0
	v_mov_b32_e32 v87, v0
	v_mov_b32_e32 v88, v0
	v_mov_b32_e32 v89, v0
	v_mov_b32_e32 v90, v0
	v_mov_b32_e32 v91, v0
	v_mov_b32_e32 v96, v0
	v_mov_b32_e32 v97, v0
	v_mov_b32_e32 v98, v0
	v_mov_b32_e32 v99, v0
	v_mov_b32_e32 v104, v0
	v_mov_b32_e32 v105, v0
	v_mov_b32_e32 v106, v0
	v_mov_b32_e32 v107, v0
	v_mov_b32_e32 v112, v0
	v_mov_b32_e32 v113, v0
	v_mov_b32_e32 v114, v0
	v_mov_b32_e32 v115, v0
	v_mov_b32_e32 v120, v0
	v_mov_b32_e32 v121, v0
	v_mov_b32_e32 v122, v0
	v_mov_b32_e32 v123, v0
	v_mov_b32_e32 v128, v0
	v_mov_b32_e32 v129, v0
	v_mov_b32_e32 v130, v0
	v_mov_b32_e32 v131, v0
	v_mov_b32_e32 v136, v0
	v_mov_b32_e32 v137, v0
	v_mov_b32_e32 v138, v0
	v_mov_b32_e32 v139, v0
	v_mov_b32_e32 v144, v0
	v_mov_b32_e32 v145, v0
	v_mov_b32_e32 v146, v0
	v_mov_b32_e32 v147, v0
	v_mov_b32_e32 v92, v0
	v_mov_b32_e32 v93, v0
	v_mov_b32_e32 v94, v0
	v_mov_b32_e32 v95, v0
	v_mov_b32_e32 v100, v0
	v_mov_b32_e32 v101, v0
	v_mov_b32_e32 v102, v0
	v_mov_b32_e32 v103, v0
	v_mov_b32_e32 v108, v0
	v_mov_b32_e32 v109, v0
	v_mov_b32_e32 v110, v0
	v_mov_b32_e32 v111, v0
	v_mov_b32_e32 v116, v0
	v_mov_b32_e32 v117, v0
	v_mov_b32_e32 v118, v0
	v_mov_b32_e32 v119, v0
	v_mov_b32_e32 v124, v0
	v_mov_b32_e32 v125, v0
	v_mov_b32_e32 v126, v0
	v_mov_b32_e32 v127, v0
	v_mov_b32_e32 v132, v0
	v_mov_b32_e32 v133, v0
	v_mov_b32_e32 v134, v0
	v_mov_b32_e32 v135, v0
	v_mov_b32_e32 v140, v0
	v_mov_b32_e32 v141, v0
	v_mov_b32_e32 v142, v0
	v_mov_b32_e32 v143, v0
	v_mov_b32_e32 v148, v0
	v_mov_b32_e32 v149, v0
	v_mov_b32_e32 v150, v0
	v_mov_b32_e32 v151, v0

;         u.pm = 112 + (idx >> 1); u.pn = 8 + (idx & 1); return true; }
; __device__ __forceinline__ void acc_zero(f32x4 (&acc)[2][2][4][2]) {
; #pragma unroll
;     for (int a = 0; a < 2; ++a)
; #pragma unroll
;         for (int b = 0; b < 2; ++b)
; #pragma unroll
;             for (int m = 0; m < 4; ++m)
; #pragma unroll
;                 for (int n = 0; n < 2; ++n) acc[a][b][m][n] = (f32x4){0.f, 0.f, 0.f, 0.f};
; }
.LBB0_584:
	s_ashr_i32 s50, s14, 1
	s_addk_i32 s50, 0x70
	s_and_b64 s[14:15], s[18:19], exec
	s_cselect_b32 s14, s50, s23
	s_ashr_i32 s15, s14, 31
	s_lshl_b64 s[14:15], s[14:15], 19
	s_add_u32 s14, s86, s14
	s_addc_u32 s15, s87, s15
	s_and_b64 vcc, exec, s[2:3]
	s_cbranch_vccnz .LBB0_587
	s_and_b64 s[52:53], s[18:19], exec
	s_cselect_b32 s23, s15, s25
	s_cselect_b32 s51, s14, s24
	s_add_u32 s24, s24, 0x40080
	s_addc_u32 s25, s25, 0
	s_add_u32 s52, s26, 0x100
	v_mov_b32_e32 v0, 0
	s_addc_u32 s53, s27, 0
	s_mov_b32 s26, 0
	v_mov_b32_e32 v1, v0
	v_mov_b32_e32 v2, v0
	v_mov_b32_e32 v3, v0
	v_mov_b32_e32 v4, v0
	v_mov_b32_e32 v5, v0
	v_mov_b32_e32 v6, v0
	v_mov_b32_e32 v7, v0
	v_mov_b32_e32 v16, v0
	v_mov_b32_e32 v17, v0
	v_mov_b32_e32 v18, v0
	v_mov_b32_e32 v19, v0
	v_mov_b32_e32 v20, v0
	v_mov_b32_e32 v21, v0
	v_mov_b32_e32 v22, v0
	v_mov_b32_e32 v23, v0
	v_mov_b32_e32 v32, v0
	v_mov_b32_e32 v33, v0
	v_mov_b32_e32 v34, v0
	v_mov_b32_e32 v35, v0
	v_mov_b32_e32 v36, v0
	v_mov_b32_e32 v37, v0
	v_mov_b32_e32 v38, v0
	v_mov_b32_e32 v39, v0
	v_mov_b32_e32 v48, v0
	v_mov_b32_e32 v49, v0
	v_mov_b32_e32 v50, v0
	v_mov_b32_e32 v51, v0
	v_mov_b32_e32 v52, v0
	v_mov_b32_e32 v53, v0
	v_mov_b32_e32 v54, v0
	v_mov_b32_e32 v55, v0
	v_mov_b32_e32 v8, v0
	v_mov_b32_e32 v9, v0
	v_mov_b32_e32 v10, v0
	v_mov_b32_e32 v11, v0
	v_mov_b32_e32 v12, v0
	v_mov_b32_e32 v13, v0
	v_mov_b32_e32 v14, v0
	v_mov_b32_e32 v15, v0
	v_mov_b32_e32 v24, v0
	v_mov_b32_e32 v25, v0
	v_mov_b32_e32 v26, v0
	v_mov_b32_e32 v27, v0
	v_mov_b32_e32 v28, v0
	v_mov_b32_e32 v29, v0
	v_mov_b32_e32 v30, v0
	v_mov_b32_e32 v31, v0
	v_mov_b32_e32 v40, v0
	v_mov_b32_e32 v41, v0
	v_mov_b32_e32 v42, v0
	v_mov_b32_e32 v43, v0
	v_mov_b32_e32 v44, v0
	v_mov_b32_e32 v45, v0
	v_mov_b32_e32 v46, v0
	v_mov_b32_e32 v47, v0
	v_mov_b32_e32 v56, v0
	v_mov_b32_e32 v57, v0
	v_mov_b32_e32 v58, v0
	v_mov_b32_e32 v59, v0
	v_mov_b32_e32 v60, v0
	v_mov_b32_e32 v61, v0
	v_mov_b32_e32 v62, v0
	v_mov_b32_e32 v63, v0
	v_mov_b32_e32 v64, v0
	v_mov_b32_e32 v65, v0
	v_mov_b32_e32 v66, v0
	v_mov_b32_e32 v67, v0
	v_mov_b32_e32 v68, v0
	v_mov_b32_e32 v69, v0
	v_mov_b32_e32 v70, v0
	v_mov_b32_e32 v71, v0
	v_mov_b32_e32 v80, v0
	v_mov_b32_e32 v81, v0
	v_mov_b32_e32 v82, v0
	v_mov_b32_e32 v83, v0
	v_mov_b32_e32 v84, v0
	v_mov_b32_e32 v85, v0
	v_mov_b32_e32 v86, v0
	v_mov_b32_e32 v87, v0
	v_mov_b32_e32 v96, v0
	v_mov_b32_e32 v97, v0
	v_mov_b32_e32 v98, v0
	v_mov_b32_e32 v99, v0
	v_mov_b32_e32 v100, v0
	v_mov_b32_e32 v101, v0
	v_mov_b32_e32 v102, v0
	v_mov_b32_e32 v103, v0
	v_mov_b32_e32 v112, v0
	v_mov_b32_e32 v113, v0
	v_mov_b32_e32 v114, v0
	v_mov_b32_e32 v115, v0
	v_mov_b32_e32 v116, v0
	v_mov_b32_e32 v117, v0
	v_mov_b32_e32 v118, v0
	v_mov_b32_e32 v119, v0
	v_mov_b32_e32 v72, v0
	v_mov_b32_e32 v73, v0
	v_mov_b32_e32 v74, v0
	v_mov_b32_e32 v75, v0
	v_mov_b32_e32 v76, v0
	v_mov_b32_e32 v77, v0
	v_mov_b32_e32 v78, v0
	v_mov_b32_e32 v79, v0
	v_mov_b32_e32 v88, v0
	v_mov_b32_e32 v89, v0
	v_mov_b32_e32 v90, v0
	v_mov_b32_e32 v91, v0
	v_mov_b32_e32 v92, v0
	v_mov_b32_e32 v93, v0
	v_mov_b32_e32 v94, v0
	v_mov_b32_e32 v95, v0
	v_mov_b32_e32 v104, v0
	v_mov_b32_e32 v105, v0
	v_mov_b32_e32 v106, v0
	v_mov_b32_e32 v107, v0
	v_mov_b32_e32 v108, v0
	v_mov_b32_e32 v109, v0
	v_mov_b32_e32 v110, v0
	v_mov_b32_e32 v111, v0
	v_mov_b32_e32 v120, v0
	v_mov_b32_e32 v121, v0
	v_mov_b32_e32 v122, v0
	v_mov_b32_e32 v123, v0
	v_mov_b32_e32 v124, v0
	v_mov_b32_e32 v125, v0
	v_mov_b32_e32 v126, v0
	v_mov_b32_e32 v127, v0

; #define LAS __attribute__((address_space(3)))
; __device__ __forceinline__ void transpose_tile(const float* W, int ldw, int srccol0, int k0, const float* gamma, bf16_t* WT, int ldwt, int dstrow0, LAS float* scr, int lane, const float* nscale = nullptr) {
;     const float ns = nscale ? nscale[dstrow0 + (lane & 31)] : 1.f;
; #pragma unroll
;     for (int i = 0; i < 32; ++i) { const int kk = 2 * i + (lane >> 5); float v = __builtin_nontemporal_load(W + (size_t)(k0 + kk) * ldw + srccol0 + (lane & 31)); if (gamma) v *= gamma[k0 + kk]; scr[kk * 33 + (lane & 31)] = v * ns; }
;     asm volatile("s_waitcnt lgkmcnt(0)" ::: "memory");
; __global__ void __launch_bounds__(512, 2) fwd_kernel(Args a) {
;     ...
;         for (int it = dw; it < IT_WGU + IT_WD + 4 * IT_WP; it += NDW) {
;             int r = it;
;             if (r < IT_WGU) { const int kb = r / 176, nb = r % 176; const int n0 = nb * 32;
;                 const float* src = (n0 & 128) ? a.in[I_FU] : a.in[I_FG]; const int sc0 = (n0 >> 8) * 128 + (n0 & 127);
;                 transpose_tile(src, FF, sc0, kb * 64, a.in[I_NF], WGU, D, n0, scr, lane); continue; } r -= IT_WGU;
.LBB0_817:
	s_andn2_b64 vcc, exec, s[4:5]
	s_cbranch_vccnz .LBB0_807
	s_mul_hi_i32 s2, s12, 0x2e8ba2e9
	s_lshr_b32 s3, s2, 31
	s_ashr_i32 s2, s2, 5
	s_add_i32 s3, s2, s3
	s_mul_i32 s2, s3, 0xffffea00
	s_add_i32 s2, s14, s2
	v_readlane_b32 s36, v241, 6
	s_bitcmp0_b32 s12, 2
	v_readlane_b32 s44, v241, 14
	v_readlane_b32 s45, v241, 15
	v_readlane_b32 s46, v241, 16
	v_readlane_b32 s47, v241, 17
	s_mul_i32 s4, s3, 0xfffff500
	s_cselect_b32 s8, s45, s47
	s_cselect_b32 s11, s44, s46
	s_add_i32 s4, s16, s4
	s_and_b32 s4, s4, 0xffffff80
	s_and_b32 s5, s2, 0x60
	s_or_b32 s4, s4, s5
	s_ashr_i32 s5, s4, 31
	s_lshl_b32 s10, s3, 6
	s_lshl_b64 s[4:5], s[4:5], 2
	s_add_u32 s4, s11, s4
	s_addc_u32 s5, s8, s5
	v_lshlrev_b32_e32 v4, 2, v0
	v_lshl_add_u64 v[14:15], s[4:5], 0, v[4:5]
	v_or_b32_e32 v16, s10, v2
	v_mad_i64_i32 v[74:75], s[4:5], v16, s24, v[14:15]
	global_load_dword v73, v[74:75], off nt
	v_cndmask_b32_e64 v4, 0, 1, s[6:7]
	v_readlane_b32 s42, v241, 12
	v_readlane_b32 s43, v241, 13
	v_cmp_ne_u32_e64 s[4:5], 1, v4
	s_andn2_b64 vcc, exec, s[6:7]
	v_readlane_b32 s37, v241, 7
	v_readlane_b32 s38, v241, 8
	v_readlane_b32 s39, v241, 9
	v_readlane_b32 s40, v241, 10
	v_readlane_b32 s41, v241, 11
	v_readlane_b32 s48, v241, 18
	v_readlane_b32 s49, v241, 19
	v_readlane_b32 s50, v241, 20
	v_readlane_b32 s51, v241, 21
	s_ashr_i32 s11, s10, 31
	v_lshl_add_u64 v[186:187], s[10:11], 0, v[2:3]
	v_lshl_add_u64 v[186:187], v[186:187], 2, s[42:43]
	v_or_b32_e32 v182, s10, v19
	v_mad_i64_i32 v[184:185], s[26:27], v182, s24, v[14:15]
	global_load_dword v112, v[184:185], off nt
	v_or_b32_e32 v182, s10, v20
	v_mad_i64_i32 v[184:185], s[26:27], v182, s24, v[14:15]
	global_load_dword v113, v[184:185], off nt
	v_or_b32_e32 v182, s10, v21
	v_mad_i64_i32 v[184:185], s[26:27], v182, s24, v[14:15]
	global_load_dword v114, v[184:185], off nt
	v_or_b32_e32 v182, s10, v22
	v_mad_i64_i32 v[184:185], s[26:27], v182, s24, v[14:15]
	global_load_dword v115, v[184:185], off nt
	v_or_b32_e32 v182, s10, v23
	v_mad_i64_i32 v[184:185], s[26:27], v182, s24, v[14:15]
	global_load_dword v116, v[184:185], off nt
	v_or_b32_e32 v182, s10, v24
	v_mad_i64_i32 v[184:185], s[26:27], v182, s24, v[14:15]
	global_load_dword v117, v[184:185], off nt
	v_or_b32_e32 v182, s10, v26
	v_mad_i64_i32 v[184:185], s[26:27], v182, s24, v[14:15]
	global_load_dword v118, v[184:185], off nt
	v_or_b32_e32 v182, s10, v27
	v_mad_i64_i32 v[184:185], s[26:27], v182, s24, v[14:15]
	global_load_dword v119, v[184:185], off nt
	v_or_b32_e32 v182, s10, v28
	v_mad_i64_i32 v[184:185], s[26:27], v182, s24, v[14:15]
	global_load_dword v120, v[184:185], off nt
	v_or_b32_e32 v182, s10, v29
	v_mad_i64_i32 v[184:185], s[26:27], v182, s24, v[14:15]
	global_load_dword v121, v[184:185], off nt
	v_or_b32_e32 v182, s10, v30
	v_mad_i64_i32 v[184:185], s[26:27], v182, s24, v[14:15]
	global_load_dword v122, v[184:185], off nt
	v_or_b32_e32 v182, s10, v31
	v_mad_i64_i32 v[184:185], s[26:27], v182, s24, v[14:15]
	global_load_dword v123, v[184:185], off nt
	v_or_b32_e32 v182, s10, v33
	v_mad_i64_i32 v[184:185], s[26:27], v182, s24, v[14:15]
	global_load_dword v124, v[184:185], off nt
	v_or_b32_e32 v182, s10, v34
	v_mad_i64_i32 v[184:185], s[26:27], v182, s24, v[14:15]
	global_load_dword v125, v[184:185], off nt
	v_or_b32_e32 v182, s10, v35
	v_mad_i64_i32 v[184:185], s[26:27], v182, s24, v[14:15]
	global_load_dword v126, v[184:185], off nt
	v_or_b32_e32 v182, s10, v36
	v_mad_i64_i32 v[184:185], s[26:27], v182, s24, v[14:15]
	global_load_dword v127, v[184:185], off nt
	v_or_b32_e32 v182, s10, v37
	v_mad_i64_i32 v[184:185], s[26:27], v182, s24, v[14:15]
	global_load_dword v128, v[184:185], off nt
	v_or_b32_e32 v182, s10, v38
	v_mad_i64_i32 v[184:185], s[26:27], v182, s24, v[14:15]
	global_load_dword v129, v[184:185], off nt
	v_or_b32_e32 v182, s10, v40
	v_mad_i64_i32 v[184:185], s[26:27], v182, s24, v[14:15]
	global_load_dword v130, v[184:185], off nt
	v_or_b32_e32 v182, s10, v41
	v_mad_i64_i32 v[184:185], s[26:27], v182, s24, v[14:15]
	global_load_dword v131, v[184:185], off nt
	v_or_b32_e32 v182, s10, v42
	v_mad_i64_i32 v[184:185], s[26:27], v182, s24, v[14:15]
	global_load_dword v132, v[184:185], off nt
	v_or_b32_e32 v182, s10, v43
	v_mad_i64_i32 v[184:185], s[26:27], v182, s24, v[14:15]
	global_load_dword v133, v[184:185], off nt
	v_or_b32_e32 v182, s10, v44
	v_mad_i64_i32 v[184:185], s[26:27], v182, s24, v[14:15]
	global_load_dword v134, v[184:185], off nt
	v_or_b32_e32 v182, s10, v45
	v_mad_i64_i32 v[184:185], s[26:27], v182, s24, v[14:15]
	global_load_dword v135, v[184:185], off nt
	v_or_b32_e32 v182, s10, v46
; #define LAS __attribute__((address_space(3)))
; __device__ __forceinline__ void transpose_tile(const float* W, int ldw, int srccol0, int k0, const float* gamma, bf16_t* WT, int ldwt, int dstrow0, LAS float* scr, int lane, const float* nscale = nullptr) {
;     const float ns = nscale ? nscale[dstrow0 + (lane & 31)] : 1.f;
; #pragma unroll
;     for (int i = 0; i < 32; ++i) { const int kk = 2 * i + (lane >> 5); float v = __builtin_nontemporal_load(W + (size_t)(k0 + kk) * ldw + srccol0 + (lane & 31)); if (gamma) v *= gamma[k0 + kk]; scr[kk * 33 + (lane & 31)] = v * ns; }
;     asm volatile("s_waitcnt lgkmcnt(0)" ::: "memory");
	v_mad_i64_i32 v[184:185], s[26:27], v182, s24, v[14:15]
	global_load_dword v136, v[184:185], off nt
	v_or_b32_e32 v182, s10, v47
	v_mad_i64_i32 v[184:185], s[26:27], v182, s24, v[14:15]
	global_load_dword v137, v[184:185], off nt
	v_or_b32_e32 v182, s10, v48
	v_mad_i64_i32 v[184:185], s[26:27], v182, s24, v[14:15]
	global_load_dword v138, v[184:185], off nt
	v_or_b32_e32 v182, s10, v49
	v_mad_i64_i32 v[184:185], s[26:27], v182, s24, v[14:15]
	global_load_dword v139, v[184:185], off nt
	v_or_b32_e32 v182, s10, v50
	v_mad_i64_i32 v[184:185], s[26:27], v182, s24, v[14:15]
	global_load_dword v140, v[184:185], off nt
	v_or_b32_e32 v182, s10, v51
	v_mad_i64_i32 v[184:185], s[26:27], v182, s24, v[14:15]
	global_load_dword v141, v[184:185], off nt
	v_or_b32_e32 v182, s10, v52
	v_mad_i64_i32 v[184:185], s[26:27], v182, s24, v[14:15]
	global_load_dword v142, v[184:185], off nt
	global_load_dword v143, v[186:187], off
	global_load_dword v144, v[186:187], off offset:8
	global_load_dword v145, v[186:187], off offset:16
	global_load_dword v146, v[186:187], off offset:24
	global_load_dword v147, v[186:187], off offset:32
	global_load_dword v148, v[186:187], off offset:40
	global_load_dword v149, v[186:187], off offset:48
	global_load_dword v150, v[186:187], off offset:56
	global_load_dword v151, v[186:187], off offset:64
	global_load_dword v152, v[186:187], off offset:72
	global_load_dword v153, v[186:187], off offset:80
	global_load_dword v154, v[186:187], off offset:88
	global_load_dword v155, v[186:187], off offset:96
	global_load_dword v156, v[186:187], off offset:104
	global_load_dword v157, v[186:187], off offset:112
	global_load_dword v158, v[186:187], off offset:120
	global_load_dword v159, v[186:187], off offset:128
	global_load_dword v160, v[186:187], off offset:136
	global_load_dword v161, v[186:187], off offset:144
	global_load_dword v162, v[186:187], off offset:152
	global_load_dword v163, v[186:187], off offset:160
	global_load_dword v164, v[186:187], off offset:168
	global_load_dword v165, v[186:187], off offset:176
	global_load_dword v166, v[186:187], off offset:184
	global_load_dword v167, v[186:187], off offset:192
	global_load_dword v168, v[186:187], off offset:200
	global_load_dword v169, v[186:187], off offset:208
	global_load_dword v170, v[186:187], off offset:216
	global_load_dword v171, v[186:187], off offset:224
	global_load_dword v172, v[186:187], off offset:232
	global_load_dword v173, v[186:187], off offset:240
	global_load_dword v174, v[186:187], off offset:248
	s_waitcnt vmcnt(0)
	v_mul_f32_e32 v73, v73, v143
	v_mul_f32_e32 v112, v112, v144
	v_mul_f32_e32 v113, v113, v145
	v_mul_f32_e32 v114, v114, v146
	v_mul_f32_e32 v115, v115, v147
	v_mul_f32_e32 v116, v116, v148
	v_mul_f32_e32 v117, v117, v149
	v_mul_f32_e32 v118, v118, v150
	v_mul_f32_e32 v119, v119, v151
	v_mul_f32_e32 v120, v120, v152
	v_mul_f32_e32 v121, v121, v153
	v_mul_f32_e32 v122, v122, v154
	v_mul_f32_e32 v123, v123, v155
	v_mul_f32_e32 v124, v124, v156
	v_mul_f32_e32 v125, v125, v157
	v_mul_f32_e32 v126, v126, v158
	v_mul_f32_e32 v127, v127, v159
	v_mul_f32_e32 v128, v128, v160
	v_mul_f32_e32 v129, v129, v161
	v_mul_f32_e32 v130, v130, v162
	v_mul_f32_e32 v131, v131, v163
	v_mul_f32_e32 v132, v132, v164
	v_mul_f32_e32 v133, v133, v165
	v_mul_f32_e32 v134, v134, v166
	v_mul_f32_e32 v135, v135, v167
	v_mul_f32_e32 v136, v136, v168
	v_mul_f32_e32 v137, v137, v169
	v_mul_f32_e32 v138, v138, v170
	v_mul_f32_e32 v139, v139, v171
	v_mul_f32_e32 v140, v140, v172
	v_mul_f32_e32 v141, v141, v173
	v_mul_f32_e32 v142, v142, v174
	v_add_u32_e32 v182, v1, v18
	ds_write_b32 v182, v73
	ds_write_b32 v58, v112
	ds_write_b32 v59, v113
	ds_write_b32 v60, v114
	ds_write_b32 v61, v115
	ds_write_b32 v62, v116
	v_add_u32_e32 v182, v1, v25
	ds_write_b32 v182, v117
	ds_write_b32 v63, v118
	ds_write_b32 v64, v119
	ds_write_b32 v65, v120
	ds_write_b32 v66, v121
	ds_write_b32 v67, v122
	v_add_u32_e32 v182, v1, v32
	ds_write_b32 v182, v123
	ds_write_b32 v68, v124
	ds_write_b32 v69, v125
	ds_write_b32 v70, v126
	ds_write_b32 v71, v127
	ds_write_b32 v72, v128
	v_add_u32_e32 v4, v1, v39
	ds_write_b32 v4, v129
	ds_write_b32 v4, v130 offset:264
	ds_write_b32 v4, v131 offset:528
	ds_write_b32 v4, v132 offset:792
	ds_write_b32 v4, v133 offset:1056
	ds_write_b32 v4, v134 offset:1320
	ds_write_b32 v4, v135 offset:1584
	ds_write_b32 v4, v136 offset:1848
	ds_write_b32 v4, v137 offset:2112
	ds_write_b32 v4, v138 offset:2376
	ds_write_b32 v4, v139 offset:2640
	ds_write_b32 v4, v140 offset:2904
	ds_write_b32 v4, v141 offset:3168
	v_mov_b32_e32 v15, v142
	s_branch .LBB0_806

; #define PG8_STAGE(bufoff, gbase, voff) do { _Pragma("unroll") for (int _i = 0; _i < 2; ++_i) \
;         __builtin_amdgcn_global_load_lds((const unsigned*)((const char*)(gbase) + (voff)[_i]), (PG8_LAS unsigned*)(lds + (bufoff) + ldsw + _i * 8192), 16, 0, 0); } while (0)
; #define PG8_WAIT_V(n) asm volatile("s_waitcnt vmcnt(" #n ")" ::: "memory")
; #define PG8_BAR __builtin_amdgcn_s_barrier()
; template <class Epi, class Sched>
; __device__ __forceinline__ void gemm_phase(PG8_LAS unsigned char* lds, const Gemm g, const Sched& S, const Epi& E) {
;     ...
;     PG8_STAGE(PG8_SB(0, 0), cB, voffB); PG8_STAGE(PG8_SB(0, 1), cB + hstepB, voffB); PG8_STAGE(PG8_SA(0, 0), cA, voffA); PG8_STAGE(PG8_SA(0, 1), cA + hstepA, voffA);
;     if (wr == 1) PG8_BAR;
;     PG8_WAIT_V(2); PG8_BAR;
;     PG8_STAGE(PG8_SB(1, 0), cB + kstep, voffB); PG8_STAGE(PG8_SA(1, 0), cA + kstep, voffA); PG8_STAGE(PG8_SB(1, 1), cB + hstepB + kstep, voffB);
;     PG8_WAIT_V(6); PG8_BAR;
;     __device__ __forceinline__ void operator()(const f32x4 (&acc)[2][2][4][2], const Unit& u, int wr, int wc, int fr, int fq) const {
;         const int col = u.pn * 128 + wc * 32 + 8 * fq; const int row0 = u.pm * 256 + wr * 64 + fr;
;         float rsv[8];
; #pragma unroll
;         for (int i = 0; i < 8; ++i) rsv[i] = ssq[row0 + (i >> 2) * 128 + (i & 3) * 16];
.LBB0_938:
	s_mov_b64 s[22:23], 0x80
	s_add_i32 m0, s40, 0x18000
	v_lshl_add_u64 v[8:9], v[8:9], 0, s[22:23]
	s_waitcnt vmcnt(2)
	s_barrier
	global_load_lds_dwordx4 v[8:9], off
	v_lshl_add_u64 v[4:5], v[4:5], 0, s[22:23]
	s_add_i32 m0, s40, 0x1a000
	s_add_i32 s45, s40, 0x8000
	global_load_lds_dwordx4 v[4:5], off
	v_lshl_add_u64 v[4:5], v[6:7], 0, s[22:23]
	s_mov_b32 m0, s45
	s_add_i32 s46, s40, 0xa000
	global_load_lds_dwordx4 v[4:5], off
	v_lshl_add_u64 v[4:5], v[10:11], 0, s[22:23]
	s_mov_b32 m0, s46
	v_lshl_add_u64 v[2:3], v[2:3], 0, s[22:23]
	global_load_lds_dwordx4 v[4:5], off
	s_add_i32 m0, s40, 0x1c000
	v_lshl_add_u64 v[0:1], v[0:1], 0, s[22:23]
	global_load_lds_dwordx4 v[2:3], off
	s_add_i32 m0, s40, 0x1e000
	s_lshr_b32 s1, s1, 26
	global_load_lds_dwordx4 v[0:1], off
	v_lshrrev_b32_e32 v1, 1, v13
	v_and_b32_e32 v1, 24, v1
	v_and_b32_e32 v0, 15, v13
	v_lshlrev_b32_e32 v2, 1, v1
	s_add_i32 s1, s0, s1
	v_lshl_or_b32 v148, s5, 6, v0
	v_lshl_or_b32 v0, v0, 6, v2
	v_lshlrev_b32_e32 v2, 2, v13
	s_ashr_i32 s47, s1, 6
	s_lshl_b32 s1, s5, 13
	v_and_b32_e32 v2, 32, v2
	v_bitop3_b32 v3, v0, s1, v2 bitop3:0xde
	s_lshl_b32 s1, s3, 5
	s_and_b32 s3, s1, 0x60
	s_lshl_b32 s1, s3, 7
	v_bitop3_b32 v149, v0, s1, v2 bitop3:0xde
	v_lshlrev_b32_e32 v0, 14, v17
	v_and_b32_e32 v0, 0xffff8000, v0
	v_or_b32_e32 v150, s3, v1
	v_lshl_add_u32 v0, v16, 11, v0
	v_and_b32_e32 v1, 1, v17
	v_lshl_or_b32 v0, v1, 6, v0
	v_lshl_add_u32 v136, v18, 1, v0
	v_lshlrev_b32_e32 v0, 14, v12
	s_cmp_gt_i32 s0, 63
	v_and_b32_e32 v0, 0xffff8000, v0
	s_cselect_b64 s[0:1], -1, 0
	s_add_i32 s48, s47, -2
	v_lshl_add_u32 v0, v14, 11, v0
	v_and_b32_e32 v1, 1, v12
	s_waitcnt vmcnt(6)
	s_cmpk_lt_u32 s2, 0x100
	v_lshl_or_b32 v0, v1, 6, v0
	s_cselect_b64 s[26:27], -1, 0
	v_lshl_add_u32 v138, v15, 1, v0
	v_cndmask_b32_e64 v0, 0, 1, s[0:1]
	s_add_i32 s49, 0, 0x10000
	s_add_i32 s50, 0, 0x14000
	s_sext_i32_i16 s9, s4
	v_mov_b32_e32 v137, v133
	v_mov_b32_e32 v139, v133
	v_mov_b64_e32 v[140:141], 0xb58
	v_mov_b64_e32 v[142:143], 0xb57
	v_cmp_ne_u32_e64 s[4:5], 1, v0
	v_add_u32_e32 v151, s49, v149
	v_add_u32_e32 v152, s50, v149
	v_add_u32_e32 v153, 0, v3
	v_mov_b32_e32 v154, 0x358637bd
	s_mov_b32 s51, 0x800000
	s_movk_i32 s52, 0x1600
	s_barrier
	v_lshl_add_u32 v253, s8, 8, v148
	v_lshlrev_b32_e32 v253, 2, v253
	global_load_dword v242, v253, s[90:91] offset:0
	global_load_dword v243, v253, s[90:91] offset:64
	global_load_dword v244, v253, s[90:91] offset:128
	global_load_dword v245, v253, s[90:91] offset:192
	global_load_dword v246, v253, s[90:91] offset:512
	global_load_dword v247, v253, s[90:91] offset:576
	global_load_dword v248, v253, s[90:91] offset:640
	global_load_dword v249, v253, s[90:91] offset:704
	s_branch .LBB0_941

;     __device__ __forceinline__ bool next(int i, Unit& u) const { u.kb = 0; u.nk = 0; return static_tile(i, nM, nN, G, c, u.pm, u.pn); }
; template <class Epi, class Sched>
; __device__ __forceinline__ void gemm_phase(PG8_LAS unsigned char* lds, const Gemm g, const Sched& S, const Epi& E) {
;     ...
;         const bool has_next = S.next(ui + 1, nxt);
;         const char* nA = has_next ? PG8_TA(nxt) : cA; const char* nB = has_next ? PG8_TB(nxt) : cB;
; __device__ __forceinline__ void acc_zero(f32x4 (&acc)[2][2][4][2]) {
; #pragma unroll
;     for (int a = 0; a < 2; ++a)
; #pragma unroll
;         for (int b = 0; b < 2; ++b)
; #pragma unroll
;             for (int m = 0; m < 4; ++m)
; #pragma unroll
;                 for (int n = 0; n < 2; ++n) acc[a][b][m][n] = (f32x4){0.f, 0.f, 0.f, 0.f};
; }
.LBB0_945:
	s_ashr_i32 s29, s28, 31
	s_lshl_b64 s[2:3], s[28:29], 19
	s_add_u32 s34, s86, s2
	s_addc_u32 s35, s87, s3
	s_and_b64 vcc, exec, s[4:5]
	s_cbranch_vccnz .LBB0_948
	s_and_b64 s[0:1], s[0:1], exec
	s_cselect_b32 s2, s35, s13
	s_cselect_b32 s3, s34, s12
	s_add_u32 s0, s12, 0x40080
	s_addc_u32 s1, s13, 0
	s_add_u32 s12, s10, 0x100
	v_mov_b32_e32 v0, 0
	s_addc_u32 s13, s11, 0
	s_mov_b32 s10, 0
	v_mov_b32_e32 v1, v0
	v_mov_b32_e32 v2, v0
	v_mov_b32_e32 v3, v0
	v_mov_b32_e32 v12, v0
	v_mov_b32_e32 v13, v0
	v_mov_b32_e32 v14, v0
	v_mov_b32_e32 v15, v0
	v_mov_b32_e32 v20, v0
	v_mov_b32_e32 v21, v0
	v_mov_b32_e32 v22, v0
	v_mov_b32_e32 v23, v0
	v_mov_b32_e32 v28, v0
	v_mov_b32_e32 v29, v0
	v_mov_b32_e32 v30, v0
	v_mov_b32_e32 v31, v0
	v_mov_b32_e32 v36, v0
	v_mov_b32_e32 v37, v0
	v_mov_b32_e32 v38, v0
	v_mov_b32_e32 v39, v0
	v_mov_b32_e32 v44, v0
	v_mov_b32_e32 v45, v0
	v_mov_b32_e32 v46, v0
	v_mov_b32_e32 v47, v0
	v_mov_b32_e32 v52, v0
	v_mov_b32_e32 v53, v0
	v_mov_b32_e32 v54, v0
	v_mov_b32_e32 v55, v0
	v_mov_b32_e32 v60, v0
	v_mov_b32_e32 v61, v0
	v_mov_b32_e32 v62, v0
	v_mov_b32_e32 v63, v0
	v_mov_b32_e32 v4, v0
	v_mov_b32_e32 v5, v0
	v_mov_b32_e32 v6, v0
	v_mov_b32_e32 v7, v0
	v_mov_b32_e32 v8, v0
	v_mov_b32_e32 v9, v0
	v_mov_b32_e32 v10, v0
	v_mov_b32_e32 v11, v0
	v_mov_b32_e32 v16, v0
	v_mov_b32_e32 v17, v0
	v_mov_b32_e32 v18, v0
	v_mov_b32_e32 v19, v0
	v_mov_b32_e32 v24, v0
	v_mov_b32_e32 v25, v0
	v_mov_b32_e32 v26, v0
	v_mov_b32_e32 v27, v0
	v_mov_b32_e32 v32, v0
	v_mov_b32_e32 v33, v0
	v_mov_b32_e32 v34, v0
	v_mov_b32_e32 v35, v0
	v_mov_b32_e32 v40, v0
	v_mov_b32_e32 v41, v0
	v_mov_b32_e32 v42, v0
	v_mov_b32_e32 v43, v0
	v_mov_b32_e32 v48, v0
	v_mov_b32_e32 v49, v0
	v_mov_b32_e32 v50, v0
	v_mov_b32_e32 v51, v0
	v_mov_b32_e32 v56, v0
	v_mov_b32_e32 v57, v0
	v_mov_b32_e32 v58, v0
	v_mov_b32_e32 v59, v0
	v_mov_b32_e32 v68, v0
	v_mov_b32_e32 v69, v0
	v_mov_b32_e32 v70, v0
	v_mov_b32_e32 v71, v0
	v_mov_b32_e32 v76, v0
	v_mov_b32_e32 v77, v0
	v_mov_b32_e32 v78, v0
	v_mov_b32_e32 v79, v0
	v_mov_b32_e32 v84, v0
	v_mov_b32_e32 v85, v0
	v_mov_b32_e32 v86, v0
	v_mov_b32_e32 v87, v0
	v_mov_b32_e32 v92, v0
	v_mov_b32_e32 v93, v0
	v_mov_b32_e32 v94, v0
	v_mov_b32_e32 v95, v0
	v_mov_b32_e32 v100, v0
	v_mov_b32_e32 v101, v0
	v_mov_b32_e32 v102, v0
	v_mov_b32_e32 v103, v0
	v_mov_b32_e32 v108, v0
	v_mov_b32_e32 v109, v0
	v_mov_b32_e32 v110, v0
	v_mov_b32_e32 v111, v0
	v_mov_b32_e32 v116, v0
	v_mov_b32_e32 v117, v0
	v_mov_b32_e32 v118, v0
	v_mov_b32_e32 v119, v0
	v_mov_b32_e32 v124, v0
	v_mov_b32_e32 v125, v0
	v_mov_b32_e32 v126, v0
	v_mov_b32_e32 v127, v0
	v_mov_b32_e32 v64, v0
	v_mov_b32_e32 v65, v0
	v_mov_b32_e32 v66, v0
	v_mov_b32_e32 v67, v0
	v_mov_b32_e32 v72, v0
	v_mov_b32_e32 v73, v0
	v_mov_b32_e32 v74, v0
	v_mov_b32_e32 v75, v0
	v_mov_b32_e32 v80, v0
	v_mov_b32_e32 v81, v0
	v_mov_b32_e32 v82, v0
	v_mov_b32_e32 v83, v0
	v_mov_b32_e32 v88, v0
	v_mov_b32_e32 v89, v0
	v_mov_b32_e32 v90, v0
	v_mov_b32_e32 v91, v0
	v_mov_b32_e32 v96, v0
	v_mov_b32_e32 v97, v0
	v_mov_b32_e32 v98, v0
	v_mov_b32_e32 v99, v0
	v_mov_b32_e32 v104, v0
	v_mov_b32_e32 v105, v0
	v_mov_b32_e32 v106, v0
	v_mov_b32_e32 v107, v0
	v_mov_b32_e32 v112, v0
	v_mov_b32_e32 v113, v0
	v_mov_b32_e32 v114, v0
	v_mov_b32_e32 v115, v0
	v_mov_b32_e32 v120, v0
	v_mov_b32_e32 v121, v0
	v_mov_b32_e32 v122, v0
	v_mov_b32_e32 v123, v0

; __device__ __forceinline__ unsigned cvt_pk_bf16(float lo, float hi) { unsigned r; asm volatile("v_cvt_pk_bf16_f32 %0, %1, %2" : "=v"(r) : "v"(lo), "v"(hi)); return r; }
;     __device__ __forceinline__ void operator()(const f32x4 (&acc)[2][2][4][2], const Unit& u, int wr, int wc, int fr, int fq) const {
;         const int col = u.pn * 128 + wc * 32 + 8 * fq; const int row0 = u.pm * 256 + wr * 64 + fr;
;         float rsv[8];
; #pragma unroll
;         for (int i = 0; i < 8; ++i) rsv[i] = ssq[row0 + (i >> 2) * 128 + (i & 3) * 16];
; #pragma unroll
;         for (int ai = 0; ai < 2; ++ai)
; #pragma unroll
;             for (int m = 0; m < 4; ++m) { const int row = row0 + ai * 128 + m * 16; const float rs = rsqrtf(rsv[ai * 4 + m] * (1.f / D) + EPS); float h[8];
; #pragma unroll
;                 for (int j = 0; j < 8; ++j) { const float gv = acc[ai][0][m][j >> 2][j & 3] * rs, uv = acc[ai][1][m][j >> 2][j & 3] * rs; h[j] = gv / (1.f + __expf(-gv)) * uv; }
;                 u32x4 w; w.x = cvt_pk_bf16(h[0], h[1]); w.y = cvt_pk_bf16(h[2], h[3]); w.z = cvt_pk_bf16(h[4], h[5]); w.w = cvt_pk_bf16(h[6], h[7]);
;                 *(u32x4*)(H + (size_t)row * FF + col) = w; }
;     }
.LBB0_950:
	s_lshl_b32 s100, s8, 8
	s_mul_i32 s101, s100, 0x1600
	s_lshl_b32 s100, s9, 8
	s_add_i32 s101, s101, s100
	s_add_u32 s98, s96, s101
	s_addc_u32 s99, s97, 0
	v_lshlrev_b32_e32 v250, 1, v150
	v_mad_u32_u24 v250, v148, s52, v250
	s_and_b64 s[100:101], s[6:7], exec
	s_cselect_b32 s100, s8, s28
	v_lshl_add_u32 v253, s100, 8, v148
	v_lshlrev_b32_e32 v253, 2, v253
	v_fmamk_f32 v252, v242, 0x3a800000, v154
	v_rsq_f32_e32 v251, v252
	global_load_dword v242, v253, s[90:91] offset:0
	v_mul_f32_e32 v124, v120, v124
	v_mul_f32_e32 v125, v121, v125
	v_mul_f32_e32 v126, v122, v126
	v_mul_f32_e32 v127, v123, v127
	v_mul_f32_e32 v116, v112, v116
	v_mul_f32_e32 v117, v113, v117
	v_mul_f32_e32 v118, v114, v118
	v_mul_f32_e32 v119, v115, v119
	v_mul_f32_e32 v251, 0xbfb8aa3b, v251
	v_mul_f32_e32 v120, v251, v120
	v_mul_f32_e32 v121, v251, v121
	v_mul_f32_e32 v122, v251, v122
	v_mul_f32_e32 v123, v251, v123
	v_mul_f32_e32 v112, v251, v112
	v_mul_f32_e32 v113, v251, v113
	v_mul_f32_e32 v114, v251, v114
	v_mul_f32_e32 v115, v251, v115
	v_exp_f32_e32 v120, v120
	v_exp_f32_e32 v121, v121
	v_exp_f32_e32 v122, v122
	v_exp_f32_e32 v123, v123
	v_exp_f32_e32 v112, v112
	v_exp_f32_e32 v113, v113
	v_exp_f32_e32 v114, v114
	v_exp_f32_e32 v115, v115
	v_fma_f32 v120, v120, v252, v252
	v_fma_f32 v121, v121, v252, v252
	v_fma_f32 v122, v122, v252, v252
	v_fma_f32 v123, v123, v252, v252
	v_fma_f32 v112, v112, v252, v252
	v_fma_f32 v113, v113, v252, v252
	v_fma_f32 v114, v114, v252, v252
	v_fma_f32 v115, v115, v252, v252
	v_rcp_f32_e32 v120, v120
	v_rcp_f32_e32 v121, v121
	v_rcp_f32_e32 v122, v122
	v_rcp_f32_e32 v123, v123
	v_rcp_f32_e32 v112, v112
	v_rcp_f32_e32 v113, v113
	v_rcp_f32_e32 v114, v114
	v_rcp_f32_e32 v115, v115
	v_mul_f32_e32 v124, v124, v120
	v_mul_f32_e32 v125, v125, v121
	v_mul_f32_e32 v126, v126, v122
	v_mul_f32_e32 v127, v127, v123
	v_mul_f32_e32 v116, v116, v112
	v_mul_f32_e32 v117, v117, v113
	v_mul_f32_e32 v118, v118, v114
	v_mul_f32_e32 v119, v119, v115
	v_cvt_pk_bf16_f32 v120, v124, v125
	v_cvt_pk_bf16_f32 v121, v126, v127
	v_cvt_pk_bf16_f32 v122, v116, v117
	v_cvt_pk_bf16_f32 v123, v118, v119
	global_store_dwordx4 v250, v[120:123], s[98:99]
	v_fmamk_f32 v252, v243, 0x3a800000, v154
	v_rsq_f32_e32 v251, v252
	global_load_dword v243, v253, s[90:91] offset:64
	v_mul_f32_e32 v108, v104, v108
	v_mul_f32_e32 v109, v105, v109
	v_mul_f32_e32 v110, v106, v110
	v_mul_f32_e32 v111, v107, v111
	v_mul_f32_e32 v100, v96, v100
	v_mul_f32_e32 v101, v97, v101
	v_mul_f32_e32 v102, v98, v102
	v_mul_f32_e32 v103, v99, v103
	v_mul_f32_e32 v251, 0xbfb8aa3b, v251
	v_mul_f32_e32 v104, v251, v104
	v_mul_f32_e32 v105, v251, v105
	v_mul_f32_e32 v106, v251, v106
	v_mul_f32_e32 v107, v251, v107
	v_mul_f32_e32 v96, v251, v96
	v_mul_f32_e32 v97, v251, v97
	v_mul_f32_e32 v98, v251, v98
	v_mul_f32_e32 v99, v251, v99
	v_exp_f32_e32 v104, v104
	v_exp_f32_e32 v105, v105
	v_exp_f32_e32 v106, v106
	v_exp_f32_e32 v107, v107
	v_exp_f32_e32 v96, v96
	v_exp_f32_e32 v97, v97
	v_exp_f32_e32 v98, v98
	v_exp_f32_e32 v99, v99
	v_fma_f32 v104, v104, v252, v252
	v_fma_f32 v105, v105, v252, v252
	v_fma_f32 v106, v106, v252, v252
	v_fma_f32 v107, v107, v252, v252
	v_fma_f32 v96, v96, v252, v252
	v_fma_f32 v97, v97, v252, v252
	v_fma_f32 v98, v98, v252, v252
	v_fma_f32 v99, v99, v252, v252
	v_rcp_f32_e32 v104, v104
	v_rcp_f32_e32 v105, v105
	v_rcp_f32_e32 v106, v106
	v_rcp_f32_e32 v107, v107
	v_rcp_f32_e32 v96, v96
	v_rcp_f32_e32 v97, v97
	v_rcp_f32_e32 v98, v98
	v_rcp_f32_e32 v99, v99
	v_mul_f32_e32 v108, v108, v104
	v_mul_f32_e32 v109, v109, v105
	v_mul_f32_e32 v110, v110, v106
	v_mul_f32_e32 v111, v111, v107
	v_mul_f32_e32 v100, v100, v96
	v_mul_f32_e32 v101, v101, v97
	v_mul_f32_e32 v102, v102, v98
	v_mul_f32_e32 v103, v103, v99
	v_cvt_pk_bf16_f32 v104, v108, v109
	v_cvt_pk_bf16_f32 v105, v110, v111
	v_cvt_pk_bf16_f32 v106, v100, v101
	v_cvt_pk_bf16_f32 v107, v102, v103
	s_add_u32 s98, s98, 0x16000
	s_addc_u32 s99, s99, 0
	global_store_dwordx4 v250, v[104:107], s[98:99]
	v_fmamk_f32 v252, v244, 0x3a800000, v154
	v_rsq_f32_e32 v251, v252
	global_load_dword v244, v253, s[90:91] offset:128
	v_mul_f32_e32 v92, v88, v92
	v_mul_f32_e32 v93, v89, v93
	v_mul_f32_e32 v94, v90, v94
	v_mul_f32_e32 v95, v91, v95
	v_mul_f32_e32 v84, v80, v84
	v_mul_f32_e32 v85, v81, v85
	v_mul_f32_e32 v86, v82, v86
	v_mul_f32_e32 v87, v83, v87
	v_mul_f32_e32 v251, 0xbfb8aa3b, v251
	v_mul_f32_e32 v88, v251, v88
	v_mul_f32_e32 v89, v251, v89
	v_mul_f32_e32 v90, v251, v90
	v_mul_f32_e32 v91, v251, v91
	v_mul_f32_e32 v80, v251, v80
	v_mul_f32_e32 v81, v251, v81
	v_mul_f32_e32 v82, v251, v82
	v_mul_f32_e32 v83, v251, v83
	v_exp_f32_e32 v88, v88
	v_exp_f32_e32 v89, v89
	v_exp_f32_e32 v90, v90
	v_exp_f32_e32 v91, v91
	v_exp_f32_e32 v80, v80
	v_exp_f32_e32 v81, v81
	v_exp_f32_e32 v82, v82
	v_exp_f32_e32 v83, v83
	v_fma_f32 v88, v88, v252, v252
	v_fma_f32 v89, v89, v252, v252
	v_fma_f32 v90, v90, v252, v252
	v_fma_f32 v91, v91, v252, v252
	v_fma_f32 v80, v80, v252, v252
	v_fma_f32 v81, v81, v252, v252
	v_fma_f32 v82, v82, v252, v252
	v_fma_f32 v83, v83, v252, v252
	v_rcp_f32_e32 v88, v88
	v_rcp_f32_e32 v89, v89
	v_rcp_f32_e32 v90, v90
	v_rcp_f32_e32 v91, v91
	v_rcp_f32_e32 v80, v80
	v_rcp_f32_e32 v81, v81
	v_rcp_f32_e32 v82, v82
	v_rcp_f32_e32 v83, v83
	v_mul_f32_e32 v92, v92, v88
	v_mul_f32_e32 v93, v93, v89
	v_mul_f32_e32 v94, v94, v90
	v_mul_f32_e32 v95, v95, v91
	v_mul_f32_e32 v84, v84, v80
	v_mul_f32_e32 v85, v85, v81
	v_mul_f32_e32 v86, v86, v82
	v_mul_f32_e32 v87, v87, v83
	v_cvt_pk_bf16_f32 v88, v92, v93
	v_cvt_pk_bf16_f32 v89, v94, v95
	v_cvt_pk_bf16_f32 v90, v84, v85
	v_cvt_pk_bf16_f32 v91, v86, v87
; __device__ __forceinline__ unsigned cvt_pk_bf16(float lo, float hi) { unsigned r; asm volatile("v_cvt_pk_bf16_f32 %0, %1, %2" : "=v"(r) : "v"(lo), "v"(hi)); return r; }
;     __device__ __forceinline__ void operator()(const f32x4 (&acc)[2][2][4][2], const Unit& u, int wr, int wc, int fr, int fq) const {
;         const int col = u.pn * 128 + wc * 32 + 8 * fq; const int row0 = u.pm * 256 + wr * 64 + fr;
;         float rsv[8];
; #pragma unroll
;         for (int i = 0; i < 8; ++i) rsv[i] = ssq[row0 + (i >> 2) * 128 + (i & 3) * 16];
; #pragma unroll
;         for (int ai = 0; ai < 2; ++ai)
; #pragma unroll
;             for (int m = 0; m < 4; ++m) { const int row = row0 + ai * 128 + m * 16; const float rs = rsqrtf(rsv[ai * 4 + m] * (1.f / D) + EPS); float h[8];
; #pragma unroll
;                 for (int j = 0; j < 8; ++j) { const float gv = acc[ai][0][m][j >> 2][j & 3] * rs, uv = acc[ai][1][m][j >> 2][j & 3] * rs; h[j] = gv / (1.f + __expf(-gv)) * uv; }
;                 u32x4 w; w.x = cvt_pk_bf16(h[0], h[1]); w.y = cvt_pk_bf16(h[2], h[3]); w.z = cvt_pk_bf16(h[4], h[5]); w.w = cvt_pk_bf16(h[6], h[7]);
;                 *(u32x4*)(H + (size_t)row * FF + col) = w; }
;     }
	s_add_u32 s98, s98, 0x16000
	s_addc_u32 s99, s99, 0
	global_store_dwordx4 v250, v[88:91], s[98:99]
	v_fmamk_f32 v252, v245, 0x3a800000, v154
	v_rsq_f32_e32 v251, v252
	global_load_dword v245, v253, s[90:91] offset:192
	v_mul_f32_e32 v76, v72, v76
	v_mul_f32_e32 v77, v73, v77
	v_mul_f32_e32 v78, v74, v78
	v_mul_f32_e32 v79, v75, v79
	v_mul_f32_e32 v68, v64, v68
	v_mul_f32_e32 v69, v65, v69
	v_mul_f32_e32 v70, v66, v70
	v_mul_f32_e32 v71, v67, v71
	v_mul_f32_e32 v251, 0xbfb8aa3b, v251
	v_mul_f32_e32 v72, v251, v72
	v_mul_f32_e32 v73, v251, v73
	v_mul_f32_e32 v74, v251, v74
	v_mul_f32_e32 v75, v251, v75
	v_mul_f32_e32 v64, v251, v64
	v_mul_f32_e32 v65, v251, v65
	v_mul_f32_e32 v66, v251, v66
	v_mul_f32_e32 v67, v251, v67
	v_exp_f32_e32 v72, v72
	v_exp_f32_e32 v73, v73
	v_exp_f32_e32 v74, v74
	v_exp_f32_e32 v75, v75
	v_exp_f32_e32 v64, v64
	v_exp_f32_e32 v65, v65
	v_exp_f32_e32 v66, v66
	v_exp_f32_e32 v67, v67
	v_fma_f32 v72, v72, v252, v252
	v_fma_f32 v73, v73, v252, v252
	v_fma_f32 v74, v74, v252, v252
	v_fma_f32 v75, v75, v252, v252
	v_fma_f32 v64, v64, v252, v252
	v_fma_f32 v65, v65, v252, v252
	v_fma_f32 v66, v66, v252, v252
	v_fma_f32 v67, v67, v252, v252
	v_rcp_f32_e32 v72, v72
	v_rcp_f32_e32 v73, v73
	v_rcp_f32_e32 v74, v74
	v_rcp_f32_e32 v75, v75
	v_rcp_f32_e32 v64, v64
	v_rcp_f32_e32 v65, v65
	v_rcp_f32_e32 v66, v66
	v_rcp_f32_e32 v67, v67
	v_mul_f32_e32 v76, v76, v72
	v_mul_f32_e32 v77, v77, v73
	v_mul_f32_e32 v78, v78, v74
	v_mul_f32_e32 v79, v79, v75
	v_mul_f32_e32 v68, v68, v64
	v_mul_f32_e32 v69, v69, v65
	v_mul_f32_e32 v70, v70, v66
	v_mul_f32_e32 v71, v71, v67
	v_cvt_pk_bf16_f32 v72, v76, v77
	v_cvt_pk_bf16_f32 v73, v78, v79
	v_cvt_pk_bf16_f32 v74, v68, v69
	v_cvt_pk_bf16_f32 v75, v70, v71
	s_add_u32 s98, s98, 0x16000
	s_addc_u32 s99, s99, 0
	global_store_dwordx4 v250, v[72:75], s[98:99]
	v_fmamk_f32 v252, v246, 0x3a800000, v154
	v_rsq_f32_e32 v251, v252
	global_load_dword v246, v253, s[90:91] offset:512
	v_mul_f32_e32 v60, v56, v60
	v_mul_f32_e32 v61, v57, v61
	v_mul_f32_e32 v62, v58, v62
	v_mul_f32_e32 v63, v59, v63
	v_mul_f32_e32 v52, v48, v52
	v_mul_f32_e32 v53, v49, v53
	v_mul_f32_e32 v54, v50, v54
	v_mul_f32_e32 v55, v51, v55
	v_mul_f32_e32 v251, 0xbfb8aa3b, v251
	v_mul_f32_e32 v56, v251, v56
	v_mul_f32_e32 v57, v251, v57
	v_mul_f32_e32 v58, v251, v58
	v_mul_f32_e32 v59, v251, v59
	v_mul_f32_e32 v48, v251, v48
	v_mul_f32_e32 v49, v251, v49
	v_mul_f32_e32 v50, v251, v50
	v_mul_f32_e32 v51, v251, v51
	v_exp_f32_e32 v56, v56
	v_exp_f32_e32 v57, v57
	v_exp_f32_e32 v58, v58
	v_exp_f32_e32 v59, v59
	v_exp_f32_e32 v48, v48
	v_exp_f32_e32 v49, v49
	v_exp_f32_e32 v50, v50
	v_exp_f32_e32 v51, v51
	v_fma_f32 v56, v56, v252, v252
	v_fma_f32 v57, v57, v252, v252
	v_fma_f32 v58, v58, v252, v252
	v_fma_f32 v59, v59, v252, v252
	v_fma_f32 v48, v48, v252, v252
	v_fma_f32 v49, v49, v252, v252
	v_fma_f32 v50, v50, v252, v252
	v_fma_f32 v51, v51, v252, v252
	v_rcp_f32_e32 v56, v56
	v_rcp_f32_e32 v57, v57
	v_rcp_f32_e32 v58, v58
	v_rcp_f32_e32 v59, v59
	v_rcp_f32_e32 v48, v48
	v_rcp_f32_e32 v49, v49
	v_rcp_f32_e32 v50, v50
	v_rcp_f32_e32 v51, v51
	v_mul_f32_e32 v60, v60, v56
	v_mul_f32_e32 v61, v61, v57
	v_mul_f32_e32 v62, v62, v58
	v_mul_f32_e32 v63, v63, v59
	v_mul_f32_e32 v52, v52, v48
	v_mul_f32_e32 v53, v53, v49
	v_mul_f32_e32 v54, v54, v50
	v_mul_f32_e32 v55, v55, v51
	v_cvt_pk_bf16_f32 v56, v60, v61
	v_cvt_pk_bf16_f32 v57, v62, v63
	v_cvt_pk_bf16_f32 v58, v52, v53
	v_cvt_pk_bf16_f32 v59, v54, v55
	s_add_u32 s98, s98, 0x6e000
	s_addc_u32 s99, s99, 0
	global_store_dwordx4 v250, v[56:59], s[98:99]
	v_fmamk_f32 v252, v247, 0x3a800000, v154
	v_rsq_f32_e32 v251, v252
	global_load_dword v247, v253, s[90:91] offset:576
	v_mul_f32_e32 v44, v40, v44
	v_mul_f32_e32 v45, v41, v45
	v_mul_f32_e32 v46, v42, v46
	v_mul_f32_e32 v47, v43, v47
	v_mul_f32_e32 v36, v32, v36
	v_mul_f32_e32 v37, v33, v37
	v_mul_f32_e32 v38, v34, v38
	v_mul_f32_e32 v39, v35, v39
	v_mul_f32_e32 v251, 0xbfb8aa3b, v251
	v_mul_f32_e32 v40, v251, v40
	v_mul_f32_e32 v41, v251, v41
	v_mul_f32_e32 v42, v251, v42
	v_mul_f32_e32 v43, v251, v43
	v_mul_f32_e32 v32, v251, v32
	v_mul_f32_e32 v33, v251, v33
	v_mul_f32_e32 v34, v251, v34
	v_mul_f32_e32 v35, v251, v35
	v_exp_f32_e32 v40, v40
	v_exp_f32_e32 v41, v41
	v_exp_f32_e32 v42, v42
	v_exp_f32_e32 v43, v43
	v_exp_f32_e32 v32, v32
	v_exp_f32_e32 v33, v33
	v_exp_f32_e32 v34, v34
	v_exp_f32_e32 v35, v35
	v_fma_f32 v40, v40, v252, v252
; __device__ __forceinline__ unsigned cvt_pk_bf16(float lo, float hi) { unsigned r; asm volatile("v_cvt_pk_bf16_f32 %0, %1, %2" : "=v"(r) : "v"(lo), "v"(hi)); return r; }
;     __device__ __forceinline__ void operator()(const f32x4 (&acc)[2][2][4][2], const Unit& u, int wr, int wc, int fr, int fq) const {
;         const int col = u.pn * 128 + wc * 32 + 8 * fq; const int row0 = u.pm * 256 + wr * 64 + fr;
;         float rsv[8];
; #pragma unroll
;         for (int i = 0; i < 8; ++i) rsv[i] = ssq[row0 + (i >> 2) * 128 + (i & 3) * 16];
; #pragma unroll
;         for (int ai = 0; ai < 2; ++ai)
; #pragma unroll
;             for (int m = 0; m < 4; ++m) { const int row = row0 + ai * 128 + m * 16; const float rs = rsqrtf(rsv[ai * 4 + m] * (1.f / D) + EPS); float h[8];
; #pragma unroll
;                 for (int j = 0; j < 8; ++j) { const float gv = acc[ai][0][m][j >> 2][j & 3] * rs, uv = acc[ai][1][m][j >> 2][j & 3] * rs; h[j] = gv / (1.f + __expf(-gv)) * uv; }
;                 u32x4 w; w.x = cvt_pk_bf16(h[0], h[1]); w.y = cvt_pk_bf16(h[2], h[3]); w.z = cvt_pk_bf16(h[4], h[5]); w.w = cvt_pk_bf16(h[6], h[7]);
;                 *(u32x4*)(H + (size_t)row * FF + col) = w; }
;     }
	v_fma_f32 v41, v41, v252, v252
	v_fma_f32 v42, v42, v252, v252
	v_fma_f32 v43, v43, v252, v252
	v_fma_f32 v32, v32, v252, v252
	v_fma_f32 v33, v33, v252, v252
	v_fma_f32 v34, v34, v252, v252
	v_fma_f32 v35, v35, v252, v252
	v_rcp_f32_e32 v40, v40
	v_rcp_f32_e32 v41, v41
	v_rcp_f32_e32 v42, v42
	v_rcp_f32_e32 v43, v43
	v_rcp_f32_e32 v32, v32
	v_rcp_f32_e32 v33, v33
	v_rcp_f32_e32 v34, v34
	v_rcp_f32_e32 v35, v35
	v_mul_f32_e32 v44, v44, v40
	v_mul_f32_e32 v45, v45, v41
	v_mul_f32_e32 v46, v46, v42
	v_mul_f32_e32 v47, v47, v43
	v_mul_f32_e32 v36, v36, v32
	v_mul_f32_e32 v37, v37, v33
	v_mul_f32_e32 v38, v38, v34
	v_mul_f32_e32 v39, v39, v35
	v_cvt_pk_bf16_f32 v40, v44, v45
	v_cvt_pk_bf16_f32 v41, v46, v47
	v_cvt_pk_bf16_f32 v42, v36, v37
	v_cvt_pk_bf16_f32 v43, v38, v39
	s_add_u32 s98, s98, 0x16000
	s_addc_u32 s99, s99, 0
	global_store_dwordx4 v250, v[40:43], s[98:99]
	v_fmamk_f32 v252, v248, 0x3a800000, v154
	v_rsq_f32_e32 v251, v252
	global_load_dword v248, v253, s[90:91] offset:640
	v_mul_f32_e32 v28, v24, v28
	v_mul_f32_e32 v29, v25, v29
	v_mul_f32_e32 v30, v26, v30
	v_mul_f32_e32 v31, v27, v31
	v_mul_f32_e32 v20, v16, v20
	v_mul_f32_e32 v21, v17, v21
	v_mul_f32_e32 v22, v18, v22
	v_mul_f32_e32 v23, v19, v23
	v_mul_f32_e32 v251, 0xbfb8aa3b, v251
	v_mul_f32_e32 v24, v251, v24
	v_mul_f32_e32 v25, v251, v25
	v_mul_f32_e32 v26, v251, v26
	v_mul_f32_e32 v27, v251, v27
	v_mul_f32_e32 v16, v251, v16
	v_mul_f32_e32 v17, v251, v17
	v_mul_f32_e32 v18, v251, v18
	v_mul_f32_e32 v19, v251, v19
	v_exp_f32_e32 v24, v24
	v_exp_f32_e32 v25, v25
	v_exp_f32_e32 v26, v26
	v_exp_f32_e32 v27, v27
	v_exp_f32_e32 v16, v16
	v_exp_f32_e32 v17, v17
	v_exp_f32_e32 v18, v18
	v_exp_f32_e32 v19, v19
	v_fma_f32 v24, v24, v252, v252
	v_fma_f32 v25, v25, v252, v252
	v_fma_f32 v26, v26, v252, v252
	v_fma_f32 v27, v27, v252, v252
	v_fma_f32 v16, v16, v252, v252
	v_fma_f32 v17, v17, v252, v252
	v_fma_f32 v18, v18, v252, v252
	v_fma_f32 v19, v19, v252, v252
	v_rcp_f32_e32 v24, v24
	v_rcp_f32_e32 v25, v25
	v_rcp_f32_e32 v26, v26
	v_rcp_f32_e32 v27, v27
	v_rcp_f32_e32 v16, v16
	v_rcp_f32_e32 v17, v17
	v_rcp_f32_e32 v18, v18
	v_rcp_f32_e32 v19, v19
	v_mul_f32_e32 v28, v28, v24
	v_mul_f32_e32 v29, v29, v25
	v_mul_f32_e32 v30, v30, v26
	v_mul_f32_e32 v31, v31, v27
	v_mul_f32_e32 v20, v20, v16
	v_mul_f32_e32 v21, v21, v17
	v_mul_f32_e32 v22, v22, v18
	v_mul_f32_e32 v23, v23, v19
	v_cvt_pk_bf16_f32 v24, v28, v29
	v_cvt_pk_bf16_f32 v25, v30, v31
	v_cvt_pk_bf16_f32 v26, v20, v21
	v_cvt_pk_bf16_f32 v27, v22, v23
	s_add_u32 s98, s98, 0x16000
	s_addc_u32 s99, s99, 0
	global_store_dwordx4 v250, v[24:27], s[98:99]
	v_fmamk_f32 v252, v249, 0x3a800000, v154
	v_rsq_f32_e32 v251, v252
	global_load_dword v249, v253, s[90:91] offset:704
	v_mul_f32_e32 v12, v8, v12
	v_mul_f32_e32 v13, v9, v13
	v_mul_f32_e32 v14, v10, v14
	v_mul_f32_e32 v15, v11, v15
	v_mul_f32_e32 v0, v4, v0
	v_mul_f32_e32 v1, v5, v1
	v_mul_f32_e32 v2, v6, v2
	v_mul_f32_e32 v3, v7, v3
	v_mul_f32_e32 v251, 0xbfb8aa3b, v251
	v_mul_f32_e32 v8, v251, v8
	v_mul_f32_e32 v9, v251, v9
	v_mul_f32_e32 v10, v251, v10
	v_mul_f32_e32 v11, v251, v11
	v_mul_f32_e32 v4, v251, v4
	v_mul_f32_e32 v5, v251, v5
	v_mul_f32_e32 v6, v251, v6
	v_mul_f32_e32 v7, v251, v7
	v_exp_f32_e32 v8, v8
	v_exp_f32_e32 v9, v9
	v_exp_f32_e32 v10, v10
	v_exp_f32_e32 v11, v11
	v_exp_f32_e32 v4, v4
	v_exp_f32_e32 v5, v5
	v_exp_f32_e32 v6, v6
	v_exp_f32_e32 v7, v7
	v_fma_f32 v8, v8, v252, v252
	v_fma_f32 v9, v9, v252, v252
	v_fma_f32 v10, v10, v252, v252
	v_fma_f32 v11, v11, v252, v252
	v_fma_f32 v4, v4, v252, v252
	v_fma_f32 v5, v5, v252, v252
	v_fma_f32 v6, v6, v252, v252
	v_fma_f32 v7, v7, v252, v252
	v_rcp_f32_e32 v8, v8
	v_rcp_f32_e32 v9, v9
	v_rcp_f32_e32 v10, v10
	v_rcp_f32_e32 v11, v11
	v_rcp_f32_e32 v4, v4
	v_rcp_f32_e32 v5, v5
	v_rcp_f32_e32 v6, v6
	v_rcp_f32_e32 v7, v7
	v_mul_f32_e32 v12, v12, v8
	v_mul_f32_e32 v13, v13, v9
	v_mul_f32_e32 v14, v14, v10
	v_mul_f32_e32 v15, v15, v11
	v_mul_f32_e32 v0, v0, v4
	v_mul_f32_e32 v1, v1, v5
	v_mul_f32_e32 v2, v2, v6
	v_mul_f32_e32 v3, v3, v7
	v_cvt_pk_bf16_f32 v8, v12, v13
	v_cvt_pk_bf16_f32 v9, v14, v15
	v_cvt_pk_bf16_f32 v10, v0, v1
	v_cvt_pk_bf16_f32 v11, v2, v3
	s_add_u32 s98, s98, 0x16000
	s_addc_u32 s99, s99, 0
	global_store_dwordx4 v250, v[8:11], s[98:99]
	s_and_b64 vcc, exec, s[6:7]
	s_mov_b64 s[0:1], -1
	s_cbranch_vccnz .LBB0_940
	s_andn2_b64 vcc, exec, s[18:19]
	s_cbranch_vccnz .LBB0_939
	s_barrier
	s_branch .LBB0_939

; #define LAS __attribute__((address_space(3)))
; __device__ __forceinline__ f32x4 bf4(u32x2 r) { return (f32x4){__uint_as_float(r.x << 16), __uint_as_float(r.x & 0xffff0000u), __uint_as_float(r.y << 16), __uint_as_float(r.y & 0xffff0000u)}; }
; template <int W, bool SAMP>
; __device__ __forceinline__ void pool_strip(const bf16_t* XRp, bf16_t* XBp, float* pout, const float* ssq2, const LAS float* ldsrs, const float* pbuf, const float* gm,
;                                            int row0, int pos0, int seq, int Tseq, int c4) {
;     ...
;     f32x4 xn[PR + W - 1];
; #pragma unroll
;     for (int j = 0; j < PR + W - 1; ++j) { const int p = pos0 - (W - 1) + j, rr = row0 - (W - 1) + j;
;         if (p >= 0) { const float rs = SAMP ? ldsrs[p] : rsqrtf(ssq2[rr] * (1.f / D) + EPS); xn[j] = bf4(*(const u32x2*)(XRp + (size_t)rr * D + c4)) * rs * gv; }
; __global__ void __launch_bounds__(512, 2) fwd_kernel(Args a) {
;     ...
;         const float* ssq2 = SSQ + M; const float* gm = a.in[I_NM] + D; const float* pbuf = a.in[I_SP]; const LAS float* ldsrs = (const LAS float*)L;
;         for (int idx = gt; idx < (MP / PR) * 256; idx += NGT) { const int strip = idx >> 8, c4 = (idx & 255) * 4; const int row0 = strip * PR, pos0 = row0 & 4095, seq = row0 >> 12;
;             switch (c4 >> 8) {
;                 case 0: pool_strip<2, false>(XB, AO, out + OFF_PP, ssq2, ldsrs, pbuf, gm, row0, pos0, seq, 4096, c4); break;
;                 case 1: pool_strip<4, false>(XB, AO, out + OFF_PP, ssq2, ldsrs, pbuf, gm, row0, pos0, seq, 4096, c4); break;
;                 case 2: pool_strip<8, false>(XB, AO, out + OFF_PP, ssq2, ldsrs, pbuf, gm, row0, pos0, seq, 4096, c4); break;
;                 default: pool_strip<16, false>(XB, AO, out + OFF_PP, ssq2, ldsrs, pbuf, gm, row0, pos0, seq, 4096, c4); break; } }
.LBB0_1136:
	s_or_b64 exec, exec, s[0:1]
	v_readlane_b32 s36, v241, 6
	v_readlane_b32 s40, v241, 10
	v_readlane_b32 s41, v241, 11
	s_mov_b64 s[8:9], s[40:41]
	s_add_u32 s8, s8, 0x1000
	s_mov_b32 s0, 0x100000
	s_addc_u32 s9, s9, 0
	v_cmp_gt_i32_e32 vcc, s0, v178
	s_waitcnt lgkmcnt(0)
	s_barrier
	v_readlane_b32 s37, v241, 7
	v_readlane_b32 s38, v241, 8
	v_readlane_b32 s39, v241, 9
	v_readlane_b32 s42, v241, 12
	v_readlane_b32 s43, v241, 13
	v_readlane_b32 s44, v241, 14
	v_readlane_b32 s45, v241, 15
	v_readlane_b32 s46, v241, 16
	v_readlane_b32 s47, v241, 17
	v_readlane_b32 s48, v241, 18
	v_readlane_b32 s49, v241, 19
	v_readlane_b32 s50, v241, 20
	v_readlane_b32 s51, v241, 21
	s_mov_b32 s100, s56
	s_cmp_lt_u32 s92, 0x41
	s_cbranch_scc1 .Lp9_norebal
	s_cmp_lt_u32 s66, 32
	s_cbranch_scc1 .Lp9_skip_prompt
	v_subrev_u32_e32 v178, 0x4000, v178
	s_sub_u32 s100, s56, 0x4000
.Lp9_norebal:
	s_and_saveexec_b64 s[12:13], vcc
	s_cbranch_execz .LBB0_1261
	s_add_u32 s14, s88, 0x10410000
	s_addc_u32 s15, s89, 0
	v_lshlrev_b32_e32 v31, 2, v178
	s_lshl_b32 s19, s100, 2
	s_mov_b64 s[16:17], 0
	v_mov_b32_e32 v29, 0
	v_mov_b32_e32 v30, 0x358637bd
	s_mov_b32 s18, 0x3a800000
	s_mov_b32 s27, 0x800000
	s_movk_i32 s29, 0xff0
	s_movk_i32 s42, 0xfef
	s_movk_i32 s43, 0xfee
	s_movk_i32 s44, 0xfed
	s_movk_i32 s45, 0xfec
	s_movk_i32 s46, 0xfeb
	s_movk_i32 s47, 0xfea
	s_movk_i32 s48, 0xfe9
	s_mov_b32 s26, 0x3e000000
	s_mov_b32 s28, 0x3e800000
	s_mov_b32 s49, 0xfffff
	s_branch .LBB0_1139
.LBB0_1138:
	s_or_b64 exec, exec, s[0:1]
	v_add_u32_e32 v178, s100, v178
	v_cmp_lt_i32_e32 vcc, s49, v178
	s_or_b64 s[16:17], vcc, s[16:17]
	v_add_u32_e32 v31, s19, v31
	s_andn2_b64 exec, exec, s[16:17]
	s_cbranch_execz .LBB0_1261
.LBB0_1139:
	v_and_b32_e32 v4, 0x3fc, v31
	v_lshlrev_b32_e32 v32, 2, v4
	global_load_dwordx4 v[0:3], v32, s[8:9]
	v_ashrrev_i32_e32 v33, 5, v178
	v_bfe_u32 v11, v31, 8, 2
	v_lshlrev_b32_e32 v28, 1, v4
	v_and_b32_e32 v10, -8, v33
	v_and_b32_e32 v118, 0xff8, v33
	v_ashrrev_i32_e32 v119, 17, v178
	v_lshl_add_u64 v[8:9], s[86:87], 0, v[28:29]
	v_cmp_lt_i32_e32 vcc, 1, v11
	s_mov_b64 s[34:35], 0
	s_and_saveexec_b64 s[0:1], vcc
	s_xor_b64 s[30:31], exec, s[0:1]
	s_cbranch_execz .LBB0_1218
	v_cmp_lt_i32_e32 vcc, 2, v11
	s_and_saveexec_b64 s[0:1], vcc
	s_xor_b64 s[6:7], exec, s[0:1]
	s_cbranch_execz .LBB0_1186
	v_add_u32_e32 v154, -15, v10
	v_ashrrev_i32_e32 v155, 31, v154
	v_lshl_add_u64 v[156:157], v[154:155], 2, s[10:11]
	global_load_dword v158, v[156:157], off
	v_lshlrev_b64 v[154:155], 11, v[154:155]
	v_lshl_add_u64 v[154:155], v[8:9], 0, v[154:155]
	global_load_dwordx2 v[160:161], v[154:155], off
	v_add_u32_e32 v154, -14, v10
	v_ashrrev_i32_e32 v155, 31, v154
	v_lshl_add_u64 v[156:157], v[154:155], 2, s[10:11]
	global_load_dword v162, v[156:157], off
	v_lshlrev_b64 v[154:155], 11, v[154:155]
	v_lshl_add_u64 v[154:155], v[8:9], 0, v[154:155]
	global_load_dwordx2 v[164:165], v[154:155], off
	v_add_u32_e32 v154, -13, v10
	v_ashrrev_i32_e32 v155, 31, v154
	v_lshl_add_u64 v[156:157], v[154:155], 2, s[10:11]
	global_load_dword v166, v[156:157], off
	v_lshlrev_b64 v[154:155], 11, v[154:155]
	v_lshl_add_u64 v[154:155], v[8:9], 0, v[154:155]
	global_load_dwordx2 v[168:169], v[154:155], off
	v_add_u32_e32 v154, -12, v10
	v_ashrrev_i32_e32 v155, 31, v154
	v_lshl_add_u64 v[156:157], v[154:155], 2, s[10:11]
	global_load_dword v170, v[156:157], off
	v_lshlrev_b64 v[154:155], 11, v[154:155]
	v_lshl_add_u64 v[154:155], v[8:9], 0, v[154:155]
	global_load_dwordx2 v[172:173], v[154:155], off
	v_add_u32_e32 v154, -11, v10
	v_ashrrev_i32_e32 v155, 31, v154
	v_lshl_add_u64 v[156:157], v[154:155], 2, s[10:11]
	global_load_dword v174, v[156:157], off
	v_lshlrev_b64 v[154:155], 11, v[154:155]
	v_lshl_add_u64 v[154:155], v[8:9], 0, v[154:155]
	global_load_dwordx2 v[182:183], v[154:155], off
	v_add_u32_e32 v154, -10, v10
	v_ashrrev_i32_e32 v155, 31, v154
	v_lshl_add_u64 v[156:157], v[154:155], 2, s[10:11]
	global_load_dword v184, v[156:157], off
	v_lshlrev_b64 v[154:155], 11, v[154:155]
	v_lshl_add_u64 v[154:155], v[8:9], 0, v[154:155]
	global_load_dwordx2 v[186:187], v[154:155], off
	v_add_u32_e32 v154, -9, v10
	v_ashrrev_i32_e32 v155, 31, v154
	v_lshl_add_u64 v[156:157], v[154:155], 2, s[10:11]
	global_load_dword v188, v[156:157], off
	v_lshlrev_b64 v[154:155], 11, v[154:155]
	v_lshl_add_u64 v[154:155], v[8:9], 0, v[154:155]
	global_load_dwordx2 v[190:191], v[154:155], off
	v_add_u32_e32 v154, -8, v10
	v_ashrrev_i32_e32 v155, 31, v154
	v_lshl_add_u64 v[156:157], v[154:155], 2, s[10:11]
	global_load_dword v192, v[156:157], off
	v_lshlrev_b64 v[154:155], 11, v[154:155]
	v_lshl_add_u64 v[154:155], v[8:9], 0, v[154:155]
	global_load_dwordx2 v[194:195], v[154:155], off
	v_add_u32_e32 v154, -7, v10
	v_ashrrev_i32_e32 v155, 31, v154
	v_lshl_add_u64 v[156:157], v[154:155], 2, s[10:11]
	global_load_dword v196, v[156:157], off
	v_lshlrev_b64 v[154:155], 11, v[154:155]
	v_lshl_add_u64 v[154:155], v[8:9], 0, v[154:155]
	global_load_dwordx2 v[198:199], v[154:155], off
	v_add_u32_e32 v154, -6, v10
	v_ashrrev_i32_e32 v155, 31, v154
	v_lshl_add_u64 v[156:157], v[154:155], 2, s[10:11]
	global_load_dword v200, v[156:157], off
	v_lshlrev_b64 v[154:155], 11, v[154:155]
	v_lshl_add_u64 v[154:155], v[8:9], 0, v[154:155]
	global_load_dwordx2 v[202:203], v[154:155], off
	v_add_u32_e32 v154, -5, v10
	v_ashrrev_i32_e32 v155, 31, v154
	v_lshl_add_u64 v[156:157], v[154:155], 2, s[10:11]
	global_load_dword v204, v[156:157], off
	v_lshlrev_b64 v[154:155], 11, v[154:155]
	v_lshl_add_u64 v[154:155], v[8:9], 0, v[154:155]
	global_load_dwordx2 v[206:207], v[154:155], off
	v_add_u32_e32 v154, -4, v10
	v_ashrrev_i32_e32 v155, 31, v154
	v_lshl_add_u64 v[156:157], v[154:155], 2, s[10:11]
	global_load_dword v208, v[156:157], off
	v_lshlrev_b64 v[154:155], 11, v[154:155]
	v_lshl_add_u64 v[154:155], v[8:9], 0, v[154:155]
	global_load_dwordx2 v[210:211], v[154:155], off
	v_add_u32_e32 v154, -3, v10
	v_ashrrev_i32_e32 v155, 31, v154
	v_lshl_add_u64 v[156:157], v[154:155], 2, s[10:11]
	global_load_dword v212, v[156:157], off
	v_lshlrev_b64 v[154:155], 11, v[154:155]
	v_lshl_add_u64 v[154:155], v[8:9], 0, v[154:155]
	global_load_dwordx2 v[214:215], v[154:155], off
	v_add_u32_e32 v154, -2, v10
	v_ashrrev_i32_e32 v155, 31, v154
	v_lshl_add_u64 v[156:157], v[154:155], 2, s[10:11]
	global_load_dword v216, v[156:157], off
	v_lshlrev_b64 v[154:155], 11, v[154:155]
	v_lshl_add_u64 v[154:155], v[8:9], 0, v[154:155]
	global_load_dwordx2 v[218:219], v[154:155], off
	v_add_u32_e32 v154, -1, v10
	v_ashrrev_i32_e32 v155, 31, v154
	v_lshl_add_u64 v[156:157], v[154:155], 2, s[10:11]
	global_load_dword v221, v[156:157], off
	v_lshlrev_b64 v[154:155], 11, v[154:155]
	v_lshl_add_u64 v[154:155], v[8:9], 0, v[154:155]
	global_load_dwordx2 v[222:223], v[154:155], off
	v_cmp_lt_u32_e32 vcc, 14, v118
	v_mov_b32_e32 v38, 0
	v_mov_b32_e32 v50, 0
	v_mov_b32_e32 v51, 0
	v_mov_b32_e32 v48, 0
	v_mov_b32_e32 v49, 0
	s_and_saveexec_b64 s[0:1], vcc
	s_cbranch_execz .LBB0_1143
; __device__ __forceinline__ f32x4 bf4(u32x2 r) { return (f32x4){__uint_as_float(r.x << 16), __uint_as_float(r.x & 0xffff0000u), __uint_as_float(r.y << 16), __uint_as_float(r.y & 0xffff0000u)}; }
; template <int W, bool SAMP>
; __device__ __forceinline__ void pool_strip(const bf16_t* XRp, bf16_t* XBp, float* pout, const float* ssq2, const LAS float* ldsrs, const float* pbuf, const float* gm,
;                                            int row0, int pos0, int seq, int Tseq, int c4) {
;     ...
;     f32x4 xn[PR + W - 1];
; #pragma unroll
;     for (int j = 0; j < PR + W - 1; ++j) { const int p = pos0 - (W - 1) + j, rr = row0 - (W - 1) + j;
;         if (p >= 0) { const float rs = SAMP ? ldsrs[p] : rsqrtf(ssq2[rr] * (1.f / D) + EPS); xn[j] = bf4(*(const u32x2*)(XRp + (size_t)rr * D + c4)) * rs * gv; }
;         else if (SAMP) xn[j] = *(const f32x4*)(pbuf + ((size_t)seq * 15 + (15 + p)) * D + c4);
;         else xn[j] = (f32x4){0.f, 0.f, 0.f, 0.f}; }
	s_waitcnt vmcnt(29)
	v_fmamk_f32 v7, v158, 0x3a800000, v30
	v_mul_f32_e32 v11, 0x4b800000, v7
	v_cmp_gt_f32_e32 vcc, s27, v7
	s_waitcnt vmcnt(28)
	v_lshlrev_b32_e32 v6, 16, v160
	v_cndmask_b32_e32 v7, v7, v11, vcc
	v_rsq_f32_e32 v11, v7
	v_and_b32_e32 v7, 0xffff0000, v160
	v_lshlrev_b32_e32 v4, 16, v161
	v_and_b32_e32 v5, 0xffff0000, v161
	v_mul_f32_e32 v12, 0x45800000, v11
	v_cndmask_b32_e32 v12, v11, v12, vcc
	v_pk_mul_f32 v[6:7], v[12:13], v[6:7] op_sel_hi:[0,1]
	v_pk_mul_f32 v[4:5], v[12:13], v[4:5] op_sel_hi:[0,1]
	v_pk_mul_f32 v[48:49], v[2:3], v[4:5]
	v_pk_mul_f32 v[50:51], v[0:1], v[6:7]
.LBB0_1143:
	s_or_b64 exec, exec, s[0:1]
	v_cmp_lt_u32_e32 vcc, 13, v118
	v_mov_b32_e32 v39, 0
	v_mov_b32_e32 v46, 0
	v_mov_b32_e32 v47, 0
	s_and_saveexec_b64 s[0:1], vcc
	s_cbranch_execz .LBB0_1145
	s_waitcnt vmcnt(27)
	v_fmamk_f32 v7, v162, 0x3a800000, v30
	v_mul_f32_e32 v11, 0x4b800000, v7
	v_cmp_gt_f32_e32 vcc, s27, v7
	s_waitcnt vmcnt(26)
	v_lshlrev_b32_e32 v6, 16, v164
	v_cndmask_b32_e32 v7, v7, v11, vcc
	v_rsq_f32_e32 v11, v7
	v_and_b32_e32 v7, 0xffff0000, v164
	v_lshlrev_b32_e32 v4, 16, v165
	v_and_b32_e32 v5, 0xffff0000, v165
	v_mul_f32_e32 v12, 0x45800000, v11
	v_cndmask_b32_e32 v12, v11, v12, vcc
	v_pk_mul_f32 v[6:7], v[12:13], v[6:7] op_sel_hi:[0,1]
	v_pk_mul_f32 v[4:5], v[12:13], v[4:5] op_sel_hi:[0,1]
	v_pk_mul_f32 v[46:47], v[2:3], v[4:5]
	v_pk_mul_f32 v[38:39], v[0:1], v[6:7]
.LBB0_1145:
	s_or_b64 exec, exec, s[0:1]
	v_cmp_lt_u32_e32 vcc, 12, v118
	v_mov_b32_e32 v24, 0
	v_mov_b32_e32 v44, 0
	v_mov_b32_e32 v45, 0
	v_mov_b32_e32 v42, 0
	v_mov_b32_e32 v43, 0
	s_and_saveexec_b64 s[0:1], vcc
	s_cbranch_execz .LBB0_1147
	s_waitcnt vmcnt(25)
	v_fmamk_f32 v7, v166, 0x3a800000, v30
	v_mul_f32_e32 v11, 0x4b800000, v7
	v_cmp_gt_f32_e32 vcc, s27, v7
	s_waitcnt vmcnt(24)
	v_lshlrev_b32_e32 v6, 16, v168
	v_cndmask_b32_e32 v7, v7, v11, vcc
	v_rsq_f32_e32 v11, v7
	v_and_b32_e32 v7, 0xffff0000, v168
	v_lshlrev_b32_e32 v4, 16, v169
	v_and_b32_e32 v5, 0xffff0000, v169
	v_mul_f32_e32 v12, 0x45800000, v11
	v_cndmask_b32_e32 v12, v11, v12, vcc
	v_pk_mul_f32 v[6:7], v[12:13], v[6:7] op_sel_hi:[0,1]
	v_pk_mul_f32 v[4:5], v[12:13], v[4:5] op_sel_hi:[0,1]
	v_pk_mul_f32 v[42:43], v[2:3], v[4:5]
	v_pk_mul_f32 v[44:45], v[0:1], v[6:7]
.LBB0_1147:
	s_or_b64 exec, exec, s[0:1]
	v_cmp_lt_u32_e32 vcc, 11, v118
	v_mov_b32_e32 v25, 0
	v_mov_b32_e32 v40, 0
	v_mov_b32_e32 v41, 0
	s_and_saveexec_b64 s[0:1], vcc
	s_cbranch_execz .LBB0_1149
	s_waitcnt vmcnt(23)
	v_fmamk_f32 v7, v170, 0x3a800000, v30
	v_mul_f32_e32 v11, 0x4b800000, v7
	v_cmp_gt_f32_e32 vcc, s27, v7
	s_waitcnt vmcnt(22)
	v_lshlrev_b32_e32 v6, 16, v172
	v_cndmask_b32_e32 v7, v7, v11, vcc
	v_rsq_f32_e32 v11, v7
	v_and_b32_e32 v7, 0xffff0000, v172
	v_lshlrev_b32_e32 v4, 16, v173
	v_and_b32_e32 v5, 0xffff0000, v173
	v_mul_f32_e32 v12, 0x45800000, v11
	v_cndmask_b32_e32 v12, v11, v12, vcc
	v_pk_mul_f32 v[6:7], v[12:13], v[6:7] op_sel_hi:[0,1]
	v_pk_mul_f32 v[4:5], v[12:13], v[4:5] op_sel_hi:[0,1]
	v_pk_mul_f32 v[40:41], v[2:3], v[4:5]
	v_pk_mul_f32 v[24:25], v[0:1], v[6:7]
.LBB0_1149:
	s_or_b64 exec, exec, s[0:1]
	v_cmp_lt_u32_e32 vcc, 10, v118
	v_mov_b32_e32 v16, 0
	v_mov_b32_e32 v36, 0
	v_mov_b32_e32 v37, 0
	v_mov_b32_e32 v26, 0
	v_mov_b32_e32 v27, 0
	s_and_saveexec_b64 s[0:1], vcc
	s_cbranch_execz .LBB0_1151
	s_waitcnt vmcnt(21)
	v_fmamk_f32 v7, v174, 0x3a800000, v30
	v_mul_f32_e32 v11, 0x4b800000, v7
	v_cmp_gt_f32_e32 vcc, s27, v7
	s_waitcnt vmcnt(20)
	v_lshlrev_b32_e32 v6, 16, v182
	v_cndmask_b32_e32 v7, v7, v11, vcc
	v_rsq_f32_e32 v11, v7
	v_and_b32_e32 v7, 0xffff0000, v182
	v_lshlrev_b32_e32 v4, 16, v183
	v_and_b32_e32 v5, 0xffff0000, v183
	v_mul_f32_e32 v12, 0x45800000, v11
	v_cndmask_b32_e32 v12, v11, v12, vcc
	v_pk_mul_f32 v[6:7], v[12:13], v[6:7] op_sel_hi:[0,1]
	v_pk_mul_f32 v[4:5], v[12:13], v[4:5] op_sel_hi:[0,1]
	v_pk_mul_f32 v[26:27], v[2:3], v[4:5]
	v_pk_mul_f32 v[36:37], v[0:1], v[6:7]
.LBB0_1151:
	s_or_b64 exec, exec, s[0:1]
	v_cmp_lt_u32_e32 vcc, 9, v118
	v_mov_b32_e32 v17, 0
	v_mov_b32_e32 v22, 0
	v_mov_b32_e32 v23, 0
	s_and_saveexec_b64 s[0:1], vcc
	s_cbranch_execz .LBB0_1153
	s_waitcnt vmcnt(19)
	v_fmamk_f32 v7, v184, 0x3a800000, v30
	v_mul_f32_e32 v11, 0x4b800000, v7
	v_cmp_gt_f32_e32 vcc, s27, v7
	s_waitcnt vmcnt(18)
	v_lshlrev_b32_e32 v6, 16, v186
	v_cndmask_b32_e32 v7, v7, v11, vcc
	v_rsq_f32_e32 v11, v7
	v_and_b32_e32 v7, 0xffff0000, v186
	v_lshlrev_b32_e32 v4, 16, v187
	v_and_b32_e32 v5, 0xffff0000, v187
	v_mul_f32_e32 v12, 0x45800000, v11
	v_cndmask_b32_e32 v12, v11, v12, vcc
	v_pk_mul_f32 v[6:7], v[12:13], v[6:7] op_sel_hi:[0,1]
	v_pk_mul_f32 v[4:5], v[12:13], v[4:5] op_sel_hi:[0,1]
	v_pk_mul_f32 v[22:23], v[2:3], v[4:5]
	v_pk_mul_f32 v[16:17], v[0:1], v[6:7]
.LBB0_1153:
	s_or_b64 exec, exec, s[0:1]
	v_cmp_lt_u32_e32 vcc, 8, v118
	v_mov_b32_e32 v56, 0
	v_mov_b32_e32 v18, 0
	v_mov_b32_e32 v19, 0
	v_mov_b32_e32 v20, 0
	v_mov_b32_e32 v21, 0
	s_and_saveexec_b64 s[0:1], vcc
	s_cbranch_execz .LBB0_1155
	s_waitcnt vmcnt(17)
	v_fmamk_f32 v7, v188, 0x3a800000, v30
	v_mul_f32_e32 v11, 0x4b800000, v7
	v_cmp_gt_f32_e32 vcc, s27, v7
	s_waitcnt vmcnt(16)
	v_lshlrev_b32_e32 v6, 16, v190
	v_cndmask_b32_e32 v7, v7, v11, vcc
	v_rsq_f32_e32 v11, v7
	v_and_b32_e32 v7, 0xffff0000, v190
	v_lshlrev_b32_e32 v4, 16, v191
	v_and_b32_e32 v5, 0xffff0000, v191
	v_mul_f32_e32 v12, 0x45800000, v11
	v_cndmask_b32_e32 v12, v11, v12, vcc
	v_pk_mul_f32 v[6:7], v[12:13], v[6:7] op_sel_hi:[0,1]
	v_pk_mul_f32 v[4:5], v[12:13], v[4:5] op_sel_hi:[0,1]
	v_pk_mul_f32 v[20:21], v[2:3], v[4:5]
	v_pk_mul_f32 v[18:19], v[0:1], v[6:7]
; __device__ __forceinline__ f32x4 bf4(u32x2 r) { return (f32x4){__uint_as_float(r.x << 16), __uint_as_float(r.x & 0xffff0000u), __uint_as_float(r.y << 16), __uint_as_float(r.y & 0xffff0000u)}; }
; template <int W, bool SAMP>
; __device__ __forceinline__ void pool_strip(const bf16_t* XRp, bf16_t* XBp, float* pout, const float* ssq2, const LAS float* ldsrs, const float* pbuf, const float* gm,
;                                            int row0, int pos0, int seq, int Tseq, int c4) {
;     ...
;     f32x4 xn[PR + W - 1];
; #pragma unroll
;     for (int j = 0; j < PR + W - 1; ++j) { const int p = pos0 - (W - 1) + j, rr = row0 - (W - 1) + j;
;         if (p >= 0) { const float rs = SAMP ? ldsrs[p] : rsqrtf(ssq2[rr] * (1.f / D) + EPS); xn[j] = bf4(*(const u32x2*)(XRp + (size_t)rr * D + c4)) * rs * gv; }
;         else if (SAMP) xn[j] = *(const f32x4*)(pbuf + ((size_t)seq * 15 + (15 + p)) * D + c4);
;         else xn[j] = (f32x4){0.f, 0.f, 0.f, 0.f}; }
.LBB0_1155:
	s_or_b64 exec, exec, s[0:1]
	v_cmp_ne_u32_e32 vcc, 0, v118
	v_mov_b32_e32 v57, 0
	v_mov_b32_e32 v62, 0
	v_mov_b32_e32 v63, 0
	s_and_saveexec_b64 s[34:35], vcc
	s_cbranch_execz .LBB0_1157
	s_waitcnt vmcnt(15)
	v_fmamk_f32 v7, v192, 0x3a800000, v30
	v_mul_f32_e32 v11, 0x4b800000, v7
	v_cmp_gt_f32_e64 s[0:1], s27, v7
	s_waitcnt vmcnt(14)
	v_lshlrev_b32_e32 v6, 16, v194
	v_cndmask_b32_e64 v7, v7, v11, s[0:1]
	v_rsq_f32_e32 v11, v7
	v_and_b32_e32 v7, 0xffff0000, v194
	v_lshlrev_b32_e32 v4, 16, v195
	v_and_b32_e32 v5, 0xffff0000, v195
	v_mul_f32_e32 v12, 0x45800000, v11
	v_cndmask_b32_e64 v12, v11, v12, s[0:1]
	v_pk_mul_f32 v[6:7], v[12:13], v[6:7] op_sel_hi:[0,1]
	v_pk_mul_f32 v[4:5], v[12:13], v[4:5] op_sel_hi:[0,1]
	v_pk_mul_f32 v[62:63], v[2:3], v[4:5]
	v_pk_mul_f32 v[56:57], v[0:1], v[6:7]
.LBB0_1157:
	s_or_b64 exec, exec, s[34:35]
	v_mov_b32_e32 v70, 0
	v_mov_b32_e32 v74, 0
	v_mov_b32_e32 v75, 0
	v_mov_b32_e32 v72, 0
	v_mov_b32_e32 v73, 0
	s_and_saveexec_b64 s[34:35], vcc
	s_cbranch_execz .LBB0_1159
	s_waitcnt vmcnt(13)
	v_fmamk_f32 v7, v196, 0x3a800000, v30
	v_mul_f32_e32 v11, 0x4b800000, v7
	v_cmp_gt_f32_e64 s[0:1], s27, v7
	s_waitcnt vmcnt(12)
	v_lshlrev_b32_e32 v6, 16, v198
	v_cndmask_b32_e64 v7, v7, v11, s[0:1]
	v_rsq_f32_e32 v11, v7
	v_and_b32_e32 v7, 0xffff0000, v198
	v_lshlrev_b32_e32 v4, 16, v199
	v_and_b32_e32 v5, 0xffff0000, v199
	v_mul_f32_e32 v12, 0x45800000, v11
	v_cndmask_b32_e64 v12, v11, v12, s[0:1]
	v_pk_mul_f32 v[6:7], v[12:13], v[6:7] op_sel_hi:[0,1]
	v_pk_mul_f32 v[4:5], v[12:13], v[4:5] op_sel_hi:[0,1]
	v_pk_mul_f32 v[72:73], v[2:3], v[4:5]
	v_pk_mul_f32 v[74:75], v[0:1], v[6:7]
.LBB0_1159:
	s_or_b64 exec, exec, s[34:35]
	v_mov_b32_e32 v71, 0
	v_mov_b32_e32 v78, 0
	v_mov_b32_e32 v79, 0
	s_and_saveexec_b64 s[34:35], vcc
	s_cbranch_execz .LBB0_1161
	s_waitcnt vmcnt(11)
	v_fmamk_f32 v7, v200, 0x3a800000, v30
	v_mul_f32_e32 v11, 0x4b800000, v7
	v_cmp_gt_f32_e64 s[0:1], s27, v7
	s_waitcnt vmcnt(10)
	v_lshlrev_b32_e32 v6, 16, v202
	v_cndmask_b32_e64 v7, v7, v11, s[0:1]
	v_rsq_f32_e32 v11, v7
	v_and_b32_e32 v7, 0xffff0000, v202
	v_lshlrev_b32_e32 v4, 16, v203
	v_and_b32_e32 v5, 0xffff0000, v203
	v_mul_f32_e32 v12, 0x45800000, v11
	v_cndmask_b32_e64 v12, v11, v12, s[0:1]
	v_pk_mul_f32 v[6:7], v[12:13], v[6:7] op_sel_hi:[0,1]
	v_pk_mul_f32 v[4:5], v[12:13], v[4:5] op_sel_hi:[0,1]
	v_pk_mul_f32 v[78:79], v[2:3], v[4:5]
	v_pk_mul_f32 v[70:71], v[0:1], v[6:7]
.LBB0_1161:
	s_or_b64 exec, exec, s[34:35]
	v_mov_b32_e32 v82, 0
	v_mov_b32_e32 v86, 0
	v_mov_b32_e32 v87, 0
	v_mov_b32_e32 v84, 0
	v_mov_b32_e32 v85, 0
	s_and_saveexec_b64 s[34:35], vcc
	s_cbranch_execz .LBB0_1163
	s_waitcnt vmcnt(9)
	v_fmamk_f32 v7, v204, 0x3a800000, v30
	v_mul_f32_e32 v11, 0x4b800000, v7
	v_cmp_gt_f32_e64 s[0:1], s27, v7
	s_waitcnt vmcnt(8)
	v_lshlrev_b32_e32 v6, 16, v206
	v_cndmask_b32_e64 v7, v7, v11, s[0:1]
	v_rsq_f32_e32 v11, v7
	v_and_b32_e32 v7, 0xffff0000, v206
	v_lshlrev_b32_e32 v4, 16, v207
	v_and_b32_e32 v5, 0xffff0000, v207
	v_mul_f32_e32 v12, 0x45800000, v11
	v_cndmask_b32_e64 v12, v11, v12, s[0:1]
	v_pk_mul_f32 v[6:7], v[12:13], v[6:7] op_sel_hi:[0,1]
	v_pk_mul_f32 v[4:5], v[12:13], v[4:5] op_sel_hi:[0,1]
	v_pk_mul_f32 v[84:85], v[2:3], v[4:5]
	v_pk_mul_f32 v[86:87], v[0:1], v[6:7]
.LBB0_1163:
	s_or_b64 exec, exec, s[34:35]
	v_mov_b32_e32 v83, 0
	v_mov_b32_e32 v92, 0
	v_mov_b32_e32 v93, 0
	s_and_saveexec_b64 s[34:35], vcc
	s_cbranch_execz .LBB0_1165
	s_waitcnt vmcnt(7)
	v_fmamk_f32 v7, v208, 0x3a800000, v30
	v_mul_f32_e32 v11, 0x4b800000, v7
	v_cmp_gt_f32_e64 s[0:1], s27, v7
	s_waitcnt vmcnt(6)
	v_lshlrev_b32_e32 v6, 16, v210
	v_cndmask_b32_e64 v7, v7, v11, s[0:1]
	v_rsq_f32_e32 v11, v7
	v_and_b32_e32 v7, 0xffff0000, v210
	v_lshlrev_b32_e32 v4, 16, v211
	v_and_b32_e32 v5, 0xffff0000, v211
	v_mul_f32_e32 v12, 0x45800000, v11
	v_cndmask_b32_e64 v12, v11, v12, s[0:1]
	v_pk_mul_f32 v[6:7], v[12:13], v[6:7] op_sel_hi:[0,1]
	v_pk_mul_f32 v[4:5], v[12:13], v[4:5] op_sel_hi:[0,1]
	v_pk_mul_f32 v[92:93], v[2:3], v[4:5]
	v_pk_mul_f32 v[82:83], v[0:1], v[6:7]
.LBB0_1165:
	s_or_b64 exec, exec, s[34:35]
	v_mov_b32_e32 v96, 0
	v_mov_b32_e32 v102, 0
	v_mov_b32_e32 v103, 0
	v_mov_b32_e32 v100, 0
	v_mov_b32_e32 v101, 0
	s_and_saveexec_b64 s[34:35], vcc
	s_cbranch_execz .LBB0_1167
	s_waitcnt vmcnt(5)
	v_fmamk_f32 v7, v212, 0x3a800000, v30
	v_mul_f32_e32 v11, 0x4b800000, v7
	v_cmp_gt_f32_e64 s[0:1], s27, v7
	s_waitcnt vmcnt(4)
	v_lshlrev_b32_e32 v6, 16, v214
	v_cndmask_b32_e64 v7, v7, v11, s[0:1]
	v_rsq_f32_e32 v11, v7
	v_and_b32_e32 v7, 0xffff0000, v214
	v_lshlrev_b32_e32 v4, 16, v215
	v_and_b32_e32 v5, 0xffff0000, v215
	v_mul_f32_e32 v12, 0x45800000, v11
	v_cndmask_b32_e64 v12, v11, v12, s[0:1]
	v_pk_mul_f32 v[6:7], v[12:13], v[6:7] op_sel_hi:[0,1]
	v_pk_mul_f32 v[4:5], v[12:13], v[4:5] op_sel_hi:[0,1]
	v_pk_mul_f32 v[100:101], v[2:3], v[4:5]
	v_pk_mul_f32 v[102:103], v[0:1], v[6:7]
.LBB0_1167:
	s_or_b64 exec, exec, s[34:35]
	v_mov_b32_e32 v97, 0
	v_mov_b32_e32 v104, 0
	v_mov_b32_e32 v105, 0
	s_and_saveexec_b64 s[34:35], vcc
	s_cbranch_execz .LBB0_1169
	s_waitcnt vmcnt(3)
	v_fmamk_f32 v7, v216, 0x3a800000, v30
	v_mul_f32_e32 v11, 0x4b800000, v7
	v_cmp_gt_f32_e64 s[0:1], s27, v7
	s_waitcnt vmcnt(2)
	v_lshlrev_b32_e32 v6, 16, v218
	v_cndmask_b32_e64 v7, v7, v11, s[0:1]
	v_rsq_f32_e32 v11, v7
	v_and_b32_e32 v7, 0xffff0000, v218
	v_lshlrev_b32_e32 v4, 16, v219
	v_and_b32_e32 v5, 0xffff0000, v219
	v_mul_f32_e32 v12, 0x45800000, v11
	v_cndmask_b32_e64 v12, v11, v12, s[0:1]
	v_pk_mul_f32 v[6:7], v[12:13], v[6:7] op_sel_hi:[0,1]
	v_pk_mul_f32 v[4:5], v[12:13], v[4:5] op_sel_hi:[0,1]
	v_pk_mul_f32 v[104:105], v[2:3], v[4:5]
	v_pk_mul_f32 v[96:97], v[0:1], v[6:7]
.LBB0_1169:
	s_or_b64 exec, exec, s[34:35]
	v_mov_b32_e32 v112, 0
	v_mov_b32_e32 v113, 0
	v_mov_b32_e32 v114, 0
	v_mov_b32_e32 v115, 0
	s_and_saveexec_b64 s[0:1], vcc
	s_cbranch_execz .LBB0_1171
	s_waitcnt vmcnt(1)
	v_fmamk_f32 v7, v221, 0x3a800000, v30
	v_mul_f32_e32 v11, 0x4b800000, v7
	v_cmp_gt_f32_e32 vcc, s27, v7
	s_waitcnt vmcnt(0)
	v_lshlrev_b32_e32 v6, 16, v222
	v_cndmask_b32_e32 v7, v7, v11, vcc
	v_rsq_f32_e32 v11, v7
	v_and_b32_e32 v7, 0xffff0000, v222
	v_lshlrev_b32_e32 v4, 16, v223
	v_and_b32_e32 v5, 0xffff0000, v223
	v_mul_f32_e32 v12, 0x45800000, v11
	v_cndmask_b32_e32 v12, v11, v12, vcc
	v_pk_mul_f32 v[6:7], v[12:13], v[6:7] op_sel_hi:[0,1]
	v_pk_mul_f32 v[4:5], v[12:13], v[4:5] op_sel_hi:[0,1]
	v_pk_mul_f32 v[114:115], v[2:3], v[4:5]
	v_pk_mul_f32 v[112:113], v[0:1], v[6:7]

; __device__ __forceinline__ f32x4 bf4(u32x2 r) { return (f32x4){__uint_as_float(r.x << 16), __uint_as_float(r.x & 0xffff0000u), __uint_as_float(r.y << 16), __uint_as_float(r.y & 0xffff0000u)}; }
; template <int W, bool SAMP>
; __device__ __forceinline__ void pool_strip(const bf16_t* XRp, bf16_t* XBp, float* pout, const float* ssq2, const LAS float* ldsrs, const float* pbuf, const float* gm,
;                                            int row0, int pos0, int seq, int Tseq, int c4) {
;     ...
;     f32x4 xn[PR + W - 1];
; #pragma unroll
;     for (int j = 0; j < PR + W - 1; ++j) { const int p = pos0 - (W - 1) + j, rr = row0 - (W - 1) + j;
;         if (p >= 0) { const float rs = SAMP ? ldsrs[p] : rsqrtf(ssq2[rr] * (1.f / D) + EPS); xn[j] = bf4(*(const u32x2*)(XRp + (size_t)rr * D + c4)) * rs * gv; }
;         else if (SAMP) xn[j] = *(const f32x4*)(pbuf + ((size_t)seq * 15 + (15 + p)) * D + c4);
;         else xn[j] = (f32x4){0.f, 0.f, 0.f, 0.f}; }
.LBB0_1186:
	s_andn2_saveexec_b64 s[36:37], s[6:7]
	s_cbranch_execz .LBB0_1216
	v_add_u32_e32 v154, -7, v10
	v_ashrrev_i32_e32 v155, 31, v154
	v_lshl_add_u64 v[156:157], v[154:155], 2, s[10:11]
	global_load_dword v158, v[156:157], off
	v_lshlrev_b64 v[154:155], 11, v[154:155]
	v_lshl_add_u64 v[154:155], v[8:9], 0, v[154:155]
	global_load_dwordx2 v[160:161], v[154:155], off
	v_add_u32_e32 v154, -6, v10
	v_ashrrev_i32_e32 v155, 31, v154
	v_lshl_add_u64 v[156:157], v[154:155], 2, s[10:11]
	global_load_dword v162, v[156:157], off
	v_lshlrev_b64 v[154:155], 11, v[154:155]
	v_lshl_add_u64 v[154:155], v[8:9], 0, v[154:155]
	global_load_dwordx2 v[164:165], v[154:155], off
	v_add_u32_e32 v154, -5, v10
	v_ashrrev_i32_e32 v155, 31, v154
	v_lshl_add_u64 v[156:157], v[154:155], 2, s[10:11]
	global_load_dword v166, v[156:157], off
	v_lshlrev_b64 v[154:155], 11, v[154:155]
	v_lshl_add_u64 v[154:155], v[8:9], 0, v[154:155]
	global_load_dwordx2 v[168:169], v[154:155], off
	v_add_u32_e32 v154, -4, v10
	v_ashrrev_i32_e32 v155, 31, v154
	v_lshl_add_u64 v[156:157], v[154:155], 2, s[10:11]
	global_load_dword v170, v[156:157], off
	v_lshlrev_b64 v[154:155], 11, v[154:155]
	v_lshl_add_u64 v[154:155], v[8:9], 0, v[154:155]
	global_load_dwordx2 v[172:173], v[154:155], off
	v_add_u32_e32 v154, -3, v10
	v_ashrrev_i32_e32 v155, 31, v154
	v_lshl_add_u64 v[156:157], v[154:155], 2, s[10:11]
	global_load_dword v174, v[156:157], off
	v_lshlrev_b64 v[154:155], 11, v[154:155]
	v_lshl_add_u64 v[154:155], v[8:9], 0, v[154:155]
	global_load_dwordx2 v[182:183], v[154:155], off
	v_add_u32_e32 v154, -2, v10
	v_ashrrev_i32_e32 v155, 31, v154
	v_lshl_add_u64 v[156:157], v[154:155], 2, s[10:11]
	global_load_dword v184, v[156:157], off
	v_lshlrev_b64 v[154:155], 11, v[154:155]
	v_lshl_add_u64 v[154:155], v[8:9], 0, v[154:155]
	global_load_dwordx2 v[186:187], v[154:155], off
	v_add_u32_e32 v154, -1, v10
	v_ashrrev_i32_e32 v155, 31, v154
	v_lshl_add_u64 v[156:157], v[154:155], 2, s[10:11]
	global_load_dword v188, v[156:157], off
	v_lshlrev_b64 v[154:155], 11, v[154:155]
	v_lshl_add_u64 v[154:155], v[8:9], 0, v[154:155]
	global_load_dwordx2 v[190:191], v[154:155], off
	v_cmp_eq_u32_e64 s[6:7], 0, v118
	v_cmp_ne_u32_e32 vcc, 0, v118
	v_mov_b32_e32 v40, 0
	v_mov_b32_e32 v58, 0
	v_mov_b32_e32 v59, 0
	v_mov_b32_e32 v54, 0
	v_mov_b32_e32 v55, 0
	s_and_saveexec_b64 s[38:39], vcc
	s_cbranch_execz .LBB0_1189
	s_waitcnt vmcnt(13)
	v_fmamk_f32 v7, v158, 0x3a800000, v30
	v_mul_f32_e32 v11, 0x4b800000, v7
	v_cmp_gt_f32_e64 s[0:1], s27, v7
	s_waitcnt vmcnt(12)
	v_lshlrev_b32_e32 v6, 16, v160
	v_cndmask_b32_e64 v7, v7, v11, s[0:1]
	v_rsq_f32_e32 v11, v7
	v_and_b32_e32 v7, 0xffff0000, v160
	v_lshlrev_b32_e32 v4, 16, v161
	v_and_b32_e32 v5, 0xffff0000, v161
	v_mul_f32_e32 v12, 0x45800000, v11
	v_cndmask_b32_e64 v12, v11, v12, s[0:1]
	v_pk_mul_f32 v[6:7], v[12:13], v[6:7] op_sel_hi:[0,1]
	v_pk_mul_f32 v[4:5], v[12:13], v[4:5] op_sel_hi:[0,1]
	v_pk_mul_f32 v[54:55], v[2:3], v[4:5]
	v_pk_mul_f32 v[58:59], v[0:1], v[6:7]
.LBB0_1189:
	s_or_b64 exec, exec, s[38:39]
	v_mov_b32_e32 v41, 0
	v_mov_b32_e32 v48, 0
	v_mov_b32_e32 v49, 0
	s_and_saveexec_b64 s[38:39], vcc
	s_cbranch_execz .LBB0_1191
	s_waitcnt vmcnt(11)
	v_fmamk_f32 v7, v162, 0x3a800000, v30
	v_mul_f32_e32 v11, 0x4b800000, v7
	v_cmp_gt_f32_e64 s[0:1], s27, v7
	s_waitcnt vmcnt(10)
	v_lshlrev_b32_e32 v6, 16, v164
	v_cndmask_b32_e64 v7, v7, v11, s[0:1]
	v_rsq_f32_e32 v11, v7
	v_and_b32_e32 v7, 0xffff0000, v164
	v_lshlrev_b32_e32 v4, 16, v165
	v_and_b32_e32 v5, 0xffff0000, v165
	v_mul_f32_e32 v12, 0x45800000, v11
	v_cndmask_b32_e64 v12, v11, v12, s[0:1]
	v_pk_mul_f32 v[6:7], v[12:13], v[6:7] op_sel_hi:[0,1]
	v_pk_mul_f32 v[4:5], v[12:13], v[4:5] op_sel_hi:[0,1]
	v_pk_mul_f32 v[48:49], v[2:3], v[4:5]
	v_pk_mul_f32 v[40:41], v[0:1], v[6:7]
; __device__ __forceinline__ f32x4 bf4(u32x2 r) { return (f32x4){__uint_as_float(r.x << 16), __uint_as_float(r.x & 0xffff0000u), __uint_as_float(r.y << 16), __uint_as_float(r.y & 0xffff0000u)}; }
; template <int W, bool SAMP>
; __device__ __forceinline__ void pool_strip(const bf16_t* XRp, bf16_t* XBp, float* pout, const float* ssq2, const LAS float* ldsrs, const float* pbuf, const float* gm,
;                                            int row0, int pos0, int seq, int Tseq, int c4) {
;     ...
;     f32x4 xn[PR + W - 1];
; #pragma unroll
;     for (int j = 0; j < PR + W - 1; ++j) { const int p = pos0 - (W - 1) + j, rr = row0 - (W - 1) + j;
;         if (p >= 0) { const float rs = SAMP ? ldsrs[p] : rsqrtf(ssq2[rr] * (1.f / D) + EPS); xn[j] = bf4(*(const u32x2*)(XRp + (size_t)rr * D + c4)) * rs * gv; }
;         else if (SAMP) xn[j] = *(const f32x4*)(pbuf + ((size_t)seq * 15 + (15 + p)) * D + c4);
;         else xn[j] = (f32x4){0.f, 0.f, 0.f, 0.f}; }
.LBB0_1191:
	s_or_b64 exec, exec, s[38:39]
	v_mov_b32_e32 v24, 0
	v_mov_b32_e32 v46, 0
	v_mov_b32_e32 v47, 0
	v_mov_b32_e32 v44, 0
	v_mov_b32_e32 v45, 0
	s_and_saveexec_b64 s[38:39], vcc
	s_cbranch_execz .LBB0_1193
	s_waitcnt vmcnt(9)
	v_fmamk_f32 v7, v166, 0x3a800000, v30
	v_mul_f32_e32 v11, 0x4b800000, v7
	v_cmp_gt_f32_e64 s[0:1], s27, v7
	s_waitcnt vmcnt(8)
	v_lshlrev_b32_e32 v6, 16, v168
	v_cndmask_b32_e64 v7, v7, v11, s[0:1]
	v_rsq_f32_e32 v11, v7
	v_and_b32_e32 v7, 0xffff0000, v168
	v_lshlrev_b32_e32 v4, 16, v169
	v_and_b32_e32 v5, 0xffff0000, v169
	v_mul_f32_e32 v12, 0x45800000, v11
	v_cndmask_b32_e64 v12, v11, v12, s[0:1]
	v_pk_mul_f32 v[6:7], v[12:13], v[6:7] op_sel_hi:[0,1]
	v_pk_mul_f32 v[4:5], v[12:13], v[4:5] op_sel_hi:[0,1]
	v_pk_mul_f32 v[44:45], v[2:3], v[4:5]
	v_pk_mul_f32 v[46:47], v[0:1], v[6:7]
.LBB0_1193:
	s_or_b64 exec, exec, s[38:39]
	v_mov_b32_e32 v25, 0
	v_mov_b32_e32 v38, 0
	v_mov_b32_e32 v39, 0
	s_and_saveexec_b64 s[38:39], vcc
	s_cbranch_execz .LBB0_1195
	s_waitcnt vmcnt(7)
	v_fmamk_f32 v7, v170, 0x3a800000, v30
	v_mul_f32_e32 v11, 0x4b800000, v7
	v_cmp_gt_f32_e64 s[0:1], s27, v7
	s_waitcnt vmcnt(6)
	v_lshlrev_b32_e32 v6, 16, v172
	v_cndmask_b32_e64 v7, v7, v11, s[0:1]
	v_rsq_f32_e32 v11, v7
	v_and_b32_e32 v7, 0xffff0000, v172
	v_lshlrev_b32_e32 v4, 16, v173
	v_and_b32_e32 v5, 0xffff0000, v173
	v_mul_f32_e32 v12, 0x45800000, v11
	v_cndmask_b32_e64 v12, v11, v12, s[0:1]
	v_pk_mul_f32 v[6:7], v[12:13], v[6:7] op_sel_hi:[0,1]
	v_pk_mul_f32 v[4:5], v[12:13], v[4:5] op_sel_hi:[0,1]
	v_pk_mul_f32 v[38:39], v[2:3], v[4:5]
	v_pk_mul_f32 v[24:25], v[0:1], v[6:7]
.LBB0_1195:
	s_or_b64 exec, exec, s[38:39]
	v_mov_b32_e32 v16, 0
	v_mov_b32_e32 v36, 0
	v_mov_b32_e32 v37, 0
	v_mov_b32_e32 v26, 0
	v_mov_b32_e32 v27, 0
	s_and_saveexec_b64 s[38:39], vcc
	s_cbranch_execz .LBB0_1197
	s_waitcnt vmcnt(5)
	v_fmamk_f32 v7, v174, 0x3a800000, v30
	v_mul_f32_e32 v11, 0x4b800000, v7
	v_cmp_gt_f32_e64 s[0:1], s27, v7
	s_waitcnt vmcnt(4)
	v_lshlrev_b32_e32 v6, 16, v182
	v_cndmask_b32_e64 v7, v7, v11, s[0:1]
	v_rsq_f32_e32 v11, v7
	v_and_b32_e32 v7, 0xffff0000, v182
	v_lshlrev_b32_e32 v4, 16, v183
	v_and_b32_e32 v5, 0xffff0000, v183
	v_mul_f32_e32 v12, 0x45800000, v11
	v_cndmask_b32_e64 v12, v11, v12, s[0:1]
	v_pk_mul_f32 v[6:7], v[12:13], v[6:7] op_sel_hi:[0,1]
	v_pk_mul_f32 v[4:5], v[12:13], v[4:5] op_sel_hi:[0,1]
	v_pk_mul_f32 v[26:27], v[2:3], v[4:5]
	v_pk_mul_f32 v[36:37], v[0:1], v[6:7]
.LBB0_1197:
	s_or_b64 exec, exec, s[38:39]
	v_mov_b32_e32 v17, 0
	v_mov_b32_e32 v22, 0
	v_mov_b32_e32 v23, 0
	s_and_saveexec_b64 s[38:39], vcc
	s_cbranch_execz .LBB0_1199
	s_waitcnt vmcnt(3)
	v_fmamk_f32 v7, v184, 0x3a800000, v30
	v_mul_f32_e32 v11, 0x4b800000, v7
	v_cmp_gt_f32_e64 s[0:1], s27, v7
	s_waitcnt vmcnt(2)
	v_lshlrev_b32_e32 v6, 16, v186
	v_cndmask_b32_e64 v7, v7, v11, s[0:1]
	v_rsq_f32_e32 v11, v7
	v_and_b32_e32 v7, 0xffff0000, v186
	v_lshlrev_b32_e32 v4, 16, v187
	v_and_b32_e32 v5, 0xffff0000, v187
	v_mul_f32_e32 v12, 0x45800000, v11
	v_cndmask_b32_e64 v12, v11, v12, s[0:1]
	v_pk_mul_f32 v[6:7], v[12:13], v[6:7] op_sel_hi:[0,1]
	v_pk_mul_f32 v[4:5], v[12:13], v[4:5] op_sel_hi:[0,1]
	v_pk_mul_f32 v[22:23], v[2:3], v[4:5]
	v_pk_mul_f32 v[16:17], v[0:1], v[6:7]
.LBB0_1199:
	s_or_b64 exec, exec, s[38:39]
	v_mov_b32_e32 v18, 0
	v_mov_b32_e32 v19, 0
	v_mov_b32_e32 v20, 0
	v_mov_b32_e32 v21, 0
	s_and_saveexec_b64 s[0:1], vcc
	s_cbranch_execz .LBB0_1201
	s_waitcnt vmcnt(1)
	v_fmamk_f32 v7, v188, 0x3a800000, v30
	v_mul_f32_e32 v11, 0x4b800000, v7
	v_cmp_gt_f32_e32 vcc, s27, v7
	s_waitcnt vmcnt(0)
	v_lshlrev_b32_e32 v6, 16, v190
	v_cndmask_b32_e32 v7, v7, v11, vcc
	v_rsq_f32_e32 v11, v7
	v_and_b32_e32 v7, 0xffff0000, v190
	v_lshlrev_b32_e32 v4, 16, v191
	v_and_b32_e32 v5, 0xffff0000, v191
	v_mul_f32_e32 v12, 0x45800000, v11
	v_cndmask_b32_e32 v12, v11, v12, vcc
	v_pk_mul_f32 v[6:7], v[12:13], v[6:7] op_sel_hi:[0,1]
	v_pk_mul_f32 v[4:5], v[12:13], v[4:5] op_sel_hi:[0,1]
	v_pk_mul_f32 v[20:21], v[2:3], v[4:5]
	v_pk_mul_f32 v[18:19], v[0:1], v[6:7]

; __device__ __forceinline__ f32x4 bf4(u32x2 r) { return (f32x4){__uint_as_float(r.x << 16), __uint_as_float(r.x & 0xffff0000u), __uint_as_float(r.y << 16), __uint_as_float(r.y & 0xffff0000u)}; }
; template <int W, bool SAMP>
; __device__ __forceinline__ void pool_strip(const bf16_t* XRp, bf16_t* XBp, float* pout, const float* ssq2, const LAS float* ldsrs, const float* pbuf, const float* gm,
;                                            int row0, int pos0, int seq, int Tseq, int c4) {
;     ...
;     f32x4 xn[PR + W - 1];
; #pragma unroll
;     for (int j = 0; j < PR + W - 1; ++j) { const int p = pos0 - (W - 1) + j, rr = row0 - (W - 1) + j;
;         if (p >= 0) { const float rs = SAMP ? ldsrs[p] : rsqrtf(ssq2[rr] * (1.f / D) + EPS); xn[j] = bf4(*(const u32x2*)(XRp + (size_t)rr * D + c4)) * rs * gv; }
;         else if (SAMP) xn[j] = *(const f32x4*)(pbuf + ((size_t)seq * 15 + (15 + p)) * D + c4);
;         else xn[j] = (f32x4){0.f, 0.f, 0.f, 0.f}; }
.LBB0_1237:
	s_andn2_saveexec_b64 s[38:39], s[6:7]
	s_cbranch_execz .LBB0_1259
	v_add_u32_e32 v154, -3, v10
	v_ashrrev_i32_e32 v155, 31, v154
	v_lshl_add_u64 v[156:157], v[154:155], 2, s[10:11]
	global_load_dword v158, v[156:157], off
	v_lshlrev_b64 v[154:155], 11, v[154:155]
	v_lshl_add_u64 v[154:155], v[8:9], 0, v[154:155]
	global_load_dwordx2 v[160:161], v[154:155], off
	v_add_u32_e32 v154, -2, v10
	v_ashrrev_i32_e32 v155, 31, v154
	v_lshl_add_u64 v[156:157], v[154:155], 2, s[10:11]
	global_load_dword v162, v[156:157], off
	v_lshlrev_b64 v[154:155], 11, v[154:155]
	v_lshl_add_u64 v[154:155], v[8:9], 0, v[154:155]
	global_load_dwordx2 v[164:165], v[154:155], off
	v_add_u32_e32 v154, -1, v10
	v_ashrrev_i32_e32 v155, 31, v154
	v_lshl_add_u64 v[156:157], v[154:155], 2, s[10:11]
	global_load_dword v166, v[156:157], off
	v_lshlrev_b64 v[154:155], 11, v[154:155]
	v_lshl_add_u64 v[154:155], v[8:9], 0, v[154:155]
	global_load_dwordx2 v[168:169], v[154:155], off
	v_cmp_eq_u32_e64 s[0:1], 0, v118
	v_cmp_ne_u32_e32 vcc, 0, v118
	v_mov_b32_e32 v20, 0
	v_mov_b32_e32 v14, 0
	v_mov_b32_e32 v15, 0
	v_mov_b32_e32 v12, 0
	v_mov_b32_e32 v13, 0
	s_and_saveexec_b64 s[40:41], vcc
	s_cbranch_execz .LBB0_1240
	s_waitcnt vmcnt(5)
	v_fmamk_f32 v7, v158, 0x3a800000, v30
	v_mul_f32_e32 v11, 0x4b800000, v7
	v_cmp_gt_f32_e64 s[6:7], s27, v7
	s_waitcnt vmcnt(4)
	v_lshlrev_b32_e32 v6, 16, v160
	v_cndmask_b32_e64 v7, v7, v11, s[6:7]
	v_rsq_f32_e32 v11, v7
	v_and_b32_e32 v7, 0xffff0000, v160
	v_lshlrev_b32_e32 v4, 16, v161
	v_and_b32_e32 v5, 0xffff0000, v161
	v_mul_f32_e32 v12, 0x45800000, v11
	v_cndmask_b32_e64 v12, v11, v12, s[6:7]
	v_pk_mul_f32 v[6:7], v[12:13], v[6:7] op_sel_hi:[0,1]
	v_pk_mul_f32 v[4:5], v[12:13], v[4:5] op_sel_hi:[0,1]
	v_pk_mul_f32 v[12:13], v[2:3], v[4:5]
	v_pk_mul_f32 v[14:15], v[0:1], v[6:7]
.LBB0_1240:
	s_or_b64 exec, exec, s[40:41]
	v_mov_b32_e32 v21, 0
	v_mov_b32_e32 v22, 0
	v_mov_b32_e32 v23, 0
	s_and_saveexec_b64 s[40:41], vcc
	s_cbranch_execz .LBB0_1242
	s_waitcnt vmcnt(3)
	v_fmamk_f32 v7, v162, 0x3a800000, v30
	v_mul_f32_e32 v11, 0x4b800000, v7
	v_cmp_gt_f32_e64 s[6:7], s27, v7
	s_waitcnt vmcnt(2)
	v_lshlrev_b32_e32 v6, 16, v164
	v_cndmask_b32_e64 v7, v7, v11, s[6:7]
	v_rsq_f32_e32 v11, v7
	v_and_b32_e32 v7, 0xffff0000, v164
	v_lshlrev_b32_e32 v4, 16, v165
	v_and_b32_e32 v5, 0xffff0000, v165
	v_mul_f32_e32 v16, 0x45800000, v11
	v_cndmask_b32_e64 v16, v11, v16, s[6:7]
	v_pk_mul_f32 v[6:7], v[16:17], v[6:7] op_sel_hi:[0,1]
	v_pk_mul_f32 v[4:5], v[16:17], v[4:5] op_sel_hi:[0,1]
	v_pk_mul_f32 v[22:23], v[2:3], v[4:5]
	v_pk_mul_f32 v[20:21], v[0:1], v[6:7]
.LBB0_1242:
	s_or_b64 exec, exec, s[40:41]
	v_mov_b32_e32 v54, 0
	v_mov_b32_e32 v55, 0
	v_mov_b32_e32 v52, 0
	v_mov_b32_e32 v53, 0
	s_and_saveexec_b64 s[6:7], vcc
	s_cbranch_execz .LBB0_1244
	s_waitcnt vmcnt(1)
	v_fmamk_f32 v7, v166, 0x3a800000, v30
	v_mul_f32_e32 v11, 0x4b800000, v7
	v_cmp_gt_f32_e32 vcc, s27, v7
	s_waitcnt vmcnt(0)
	v_lshlrev_b32_e32 v6, 16, v168
	v_cndmask_b32_e32 v7, v7, v11, vcc
	v_rsq_f32_e32 v11, v7
	v_and_b32_e32 v7, 0xffff0000, v168
	v_lshlrev_b32_e32 v4, 16, v169
	v_and_b32_e32 v5, 0xffff0000, v169
	v_mul_f32_e32 v16, 0x45800000, v11
	v_cndmask_b32_e32 v16, v11, v16, vcc
	v_pk_mul_f32 v[6:7], v[16:17], v[6:7] op_sel_hi:[0,1]
	v_pk_mul_f32 v[4:5], v[16:17], v[4:5] op_sel_hi:[0,1]
	v_pk_mul_f32 v[52:53], v[2:3], v[4:5]
	v_pk_mul_f32 v[54:55], v[0:1], v[6:7]

; __global__ void __launch_bounds__(512, 2) fwd_kernel(Args a) {
;     ...
;         for (int idx = gt; idx < (MP / PR) * 256; idx += NGT) { const int strip = idx >> 8, c4 = (idx & 255) * 4; const int row0 = strip * PR, pos0 = row0 & 4095, seq = row0 >> 12;
;             switch (c4 >> 8) {
;                 case 0: pool_strip<2, false>(XB, AO, out + OFF_PP, ssq2, ldsrs, pbuf, gm, row0, pos0, seq, 4096, c4); break;
;                 case 1: pool_strip<4, false>(XB, AO, out + OFF_PP, ssq2, ldsrs, pbuf, gm, row0, pos0, seq, 4096, c4); break;
;                 case 2: pool_strip<8, false>(XB, AO, out + OFF_PP, ssq2, ldsrs, pbuf, gm, row0, pos0, seq, 4096, c4); break;
;                 default: pool_strip<16, false>(XB, AO, out + OFF_PP, ssq2, ldsrs, pbuf, gm, row0, pos0, seq, 4096, c4); break; } }
;         for (int sidx = bx; sidx < 32; sidx += G) {
.Lp9_skip_prompt:
	s_mov_b64 s[12:13], exec

; #define PG8_STAGE(bufoff, gbase, voff) do { _Pragma("unroll") for (int _i = 0; _i < 2; ++_i) \
;         __builtin_amdgcn_global_load_lds((const unsigned*)((const char*)(gbase) + (voff)[_i]), (PG8_LAS unsigned*)(lds + (bufoff) + ldsw + _i * 8192), 16, 0, 0); } while (0)
; #define PG8_WAIT_V(n) asm volatile("s_waitcnt vmcnt(" #n ")" ::: "memory")
; #define PG8_BAR __builtin_amdgcn_s_barrier()
; template <class Epi, class Sched>
; __device__ __forceinline__ void gemm_phase(PG8_LAS unsigned char* lds, const Gemm g, const Sched& S, const Epi& E) {
;     ...
;     PG8_STAGE(PG8_SB(0, 0), cB, voffB); PG8_STAGE(PG8_SB(0, 1), cB + hstepB, voffB); PG8_STAGE(PG8_SA(0, 0), cA, voffA); PG8_STAGE(PG8_SA(0, 1), cA + hstepA, voffA);
;     if (wr == 1) PG8_BAR;
;     PG8_WAIT_V(2); PG8_BAR;
;     PG8_STAGE(PG8_SB(1, 0), cB + kstep, voffB); PG8_STAGE(PG8_SA(1, 0), cA + kstep, voffA); PG8_STAGE(PG8_SB(1, 1), cB + hstepB + kstep, voffB);
;     PG8_WAIT_V(6); PG8_BAR;
;     __device__ __forceinline__ void operator()(const f32x4 (&acc)[2][2][4][2], const Unit& u, int wr, int wc, int fr, int fq) const {
;         const int col = u.pn * 128 + wc * 32 + 8 * fq; const int row0 = u.pm * 256 + wr * 64 + fr;
;         float rsv[8];
; #pragma unroll
;         for (int i = 0; i < 8; ++i) rsv[i] = ssq[row0 + (i >> 2) * 128 + (i & 3) * 16];
.LBB0_1592:
	s_mov_b64 s[24:25], 0x80
	s_add_i32 m0, s40, 0x18000
	v_lshl_add_u64 v[8:9], v[8:9], 0, s[24:25]
	s_waitcnt vmcnt(2)
	s_barrier
	global_load_lds_dwordx4 v[8:9], off
	v_lshl_add_u64 v[4:5], v[4:5], 0, s[24:25]
	s_add_i32 m0, s40, 0x1a000
	s_add_i32 s45, s40, 0x8000
	global_load_lds_dwordx4 v[4:5], off
	v_lshl_add_u64 v[4:5], v[6:7], 0, s[24:25]
	s_mov_b32 m0, s45
	s_add_i32 s46, s40, 0xa000
	global_load_lds_dwordx4 v[4:5], off
	v_lshl_add_u64 v[4:5], v[10:11], 0, s[24:25]
	s_mov_b32 m0, s46
	v_lshl_add_u64 v[2:3], v[2:3], 0, s[24:25]
	global_load_lds_dwordx4 v[4:5], off
	s_add_i32 m0, s40, 0x1c000
	v_lshl_add_u64 v[0:1], v[0:1], 0, s[24:25]
	global_load_lds_dwordx4 v[2:3], off
	s_add_i32 m0, s40, 0x1e000
	s_lshr_b32 s1, s1, 26
	global_load_lds_dwordx4 v[0:1], off
	v_lshrrev_b32_e32 v1, 1, v13
	v_and_b32_e32 v1, 24, v1
	v_and_b32_e32 v0, 15, v13
	v_lshlrev_b32_e32 v2, 1, v1
	s_add_i32 s1, s0, s1
	v_lshl_or_b32 v131, s7, 6, v0
	v_lshl_or_b32 v0, v0, 6, v2
	v_lshlrev_b32_e32 v2, 2, v13
	s_ashr_i32 s47, s1, 6
	s_lshl_b32 s1, s7, 13
	v_and_b32_e32 v2, 32, v2
	v_bitop3_b32 v3, v0, s1, v2 bitop3:0xde
	s_lshl_b32 s1, s6, 5
	s_sext_i32_i16 s9, s2
	s_and_b32 s2, s1, 0x60
	s_lshl_b32 s1, s2, 7
	v_bitop3_b32 v150, v0, s1, v2 bitop3:0xde
	v_lshlrev_b32_e32 v0, 14, v17
	v_and_b32_e32 v0, 0xffff8000, v0
	v_or_b32_e32 v151, s2, v1
	v_lshl_add_u32 v0, v16, 11, v0
	v_and_b32_e32 v1, 1, v17
	v_lshl_or_b32 v0, v1, 6, v0
	v_lshl_add_u32 v138, v18, 1, v0
	v_lshlrev_b32_e32 v0, 14, v12
	s_cmp_gt_i32 s0, 63
	v_and_b32_e32 v0, 0xffff8000, v0
	s_cselect_b64 s[0:1], -1, 0
	s_add_i32 s48, s47, -2
	v_lshl_add_u32 v0, v14, 11, v0
	v_and_b32_e32 v1, 1, v12
	s_waitcnt vmcnt(6)
	s_cmpk_lt_u32 s3, 0x100
	v_lshl_or_b32 v0, v1, 6, v0
	s_cselect_b64 s[26:27], -1, 0
	v_lshl_add_u32 v140, v15, 1, v0
	v_cndmask_b32_e64 v0, 0, 1, s[0:1]
	s_add_i32 s49, 0, 0x10000
	s_add_i32 s50, 0, 0x14000
	v_mov_b32_e32 v139, v135
	v_mov_b32_e32 v141, v135
	v_mov_b64_e32 v[142:143], 0xb58
	v_mov_b64_e32 v[144:145], 0xb57
	v_cmp_ne_u32_e64 s[2:3], 1, v0
	v_add_u32_e32 v152, s49, v150
	v_add_u32_e32 v153, s50, v150
	v_add_u32_e32 v154, 0, v3
	v_mov_b32_e32 v155, 0x358637bd
	s_mov_b32 s51, 0x800000
	s_movk_i32 s52, 0x1600
	s_barrier
	v_lshl_add_u32 v253, s8, 8, v131
	v_lshlrev_b32_e32 v253, 2, v253
	global_load_dword v242, v253, s[14:15] offset:0
	global_load_dword v243, v253, s[14:15] offset:64
	global_load_dword v244, v253, s[14:15] offset:128
	global_load_dword v245, v253, s[14:15] offset:192
	global_load_dword v246, v253, s[14:15] offset:512
	global_load_dword v247, v253, s[14:15] offset:576
	global_load_dword v248, v253, s[14:15] offset:640
	global_load_dword v249, v253, s[14:15] offset:704
	s_branch .LBB0_1595

;     __device__ __forceinline__ bool next(int i, Unit& u) const { u.kb = 0; u.nk = 0; return static_tile(i, nM, nN, G, c, u.pm, u.pn); }
; template <class Epi, class Sched>
; __device__ __forceinline__ void gemm_phase(PG8_LAS unsigned char* lds, const Gemm g, const Sched& S, const Epi& E) {
;     ...
;         const bool has_next = S.next(ui + 1, nxt);
;         const char* nA = has_next ? PG8_TA(nxt) : cA; const char* nB = has_next ? PG8_TB(nxt) : cB;
; __device__ __forceinline__ void acc_zero(f32x4 (&acc)[2][2][4][2]) {
; #pragma unroll
;     for (int a = 0; a < 2; ++a)
; #pragma unroll
;         for (int b = 0; b < 2; ++b)
; #pragma unroll
;             for (int m = 0; m < 4; ++m)
; #pragma unroll
;                 for (int n = 0; n < 2; ++n) acc[a][b][m][n] = (f32x4){0.f, 0.f, 0.f, 0.f};
; }
.LBB0_1599:
	s_ashr_i32 s29, s28, 31
	s_lshl_b64 s[34:35], s[28:29], 19
	s_add_u32 s34, s86, s34
	s_addc_u32 s35, s87, s35
	s_and_b64 vcc, exec, s[2:3]
	s_cbranch_vccnz .LBB0_1602
	s_and_b64 s[0:1], s[0:1], exec
	s_cselect_b32 s29, s35, s13
	s_cselect_b32 s33, s34, s12
	s_add_u32 s0, s12, 0x40080
	s_addc_u32 s1, s13, 0
	s_add_u32 s12, s10, 0x100
	v_mov_b32_e32 v0, 0
	s_addc_u32 s13, s11, 0
	s_mov_b32 s10, 0
	v_mov_b32_e32 v1, v0
	v_mov_b32_e32 v2, v0
	v_mov_b32_e32 v3, v0
	v_mov_b32_e32 v12, v0
	v_mov_b32_e32 v13, v0
	v_mov_b32_e32 v14, v0
	v_mov_b32_e32 v15, v0
	v_mov_b32_e32 v20, v0
	v_mov_b32_e32 v21, v0
	v_mov_b32_e32 v22, v0
	v_mov_b32_e32 v23, v0
	v_mov_b32_e32 v28, v0
	v_mov_b32_e32 v29, v0
	v_mov_b32_e32 v30, v0
	v_mov_b32_e32 v31, v0
	v_mov_b32_e32 v36, v0
	v_mov_b32_e32 v37, v0
	v_mov_b32_e32 v38, v0
	v_mov_b32_e32 v39, v0
	v_mov_b32_e32 v44, v0
	v_mov_b32_e32 v45, v0
	v_mov_b32_e32 v46, v0
	v_mov_b32_e32 v47, v0
	v_mov_b32_e32 v52, v0
	v_mov_b32_e32 v53, v0
	v_mov_b32_e32 v54, v0
	v_mov_b32_e32 v55, v0
	v_mov_b32_e32 v60, v0
	v_mov_b32_e32 v61, v0
	v_mov_b32_e32 v62, v0
	v_mov_b32_e32 v63, v0
	v_mov_b32_e32 v4, v0
	v_mov_b32_e32 v5, v0
	v_mov_b32_e32 v6, v0
	v_mov_b32_e32 v7, v0
	v_mov_b32_e32 v8, v0
	v_mov_b32_e32 v9, v0
	v_mov_b32_e32 v10, v0
	v_mov_b32_e32 v11, v0
	v_mov_b32_e32 v16, v0
	v_mov_b32_e32 v17, v0
	v_mov_b32_e32 v18, v0
	v_mov_b32_e32 v19, v0
	v_mov_b32_e32 v24, v0
	v_mov_b32_e32 v25, v0
	v_mov_b32_e32 v26, v0
	v_mov_b32_e32 v27, v0
	v_mov_b32_e32 v32, v0
	v_mov_b32_e32 v33, v0
	v_mov_b32_e32 v34, v0
	v_mov_b32_e32 v35, v0
	v_mov_b32_e32 v40, v0
	v_mov_b32_e32 v41, v0
	v_mov_b32_e32 v42, v0
	v_mov_b32_e32 v43, v0
	v_mov_b32_e32 v48, v0
	v_mov_b32_e32 v49, v0
	v_mov_b32_e32 v50, v0
	v_mov_b32_e32 v51, v0
	v_mov_b32_e32 v56, v0
	v_mov_b32_e32 v57, v0
	v_mov_b32_e32 v58, v0
	v_mov_b32_e32 v59, v0
	v_mov_b32_e32 v68, v0
	v_mov_b32_e32 v69, v0
	v_mov_b32_e32 v70, v0
	v_mov_b32_e32 v71, v0
	v_mov_b32_e32 v76, v0
	v_mov_b32_e32 v77, v0
	v_mov_b32_e32 v78, v0
	v_mov_b32_e32 v79, v0
	v_mov_b32_e32 v84, v0
	v_mov_b32_e32 v85, v0
	v_mov_b32_e32 v86, v0
	v_mov_b32_e32 v87, v0
	v_mov_b32_e32 v92, v0
	v_mov_b32_e32 v93, v0
	v_mov_b32_e32 v94, v0
	v_mov_b32_e32 v95, v0
	v_mov_b32_e32 v100, v0
	v_mov_b32_e32 v101, v0
	v_mov_b32_e32 v102, v0
	v_mov_b32_e32 v103, v0
	v_mov_b32_e32 v108, v0
	v_mov_b32_e32 v109, v0
	v_mov_b32_e32 v110, v0
	v_mov_b32_e32 v111, v0
	v_mov_b32_e32 v116, v0
	v_mov_b32_e32 v117, v0
	v_mov_b32_e32 v118, v0
	v_mov_b32_e32 v119, v0
	v_mov_b32_e32 v124, v0
	v_mov_b32_e32 v125, v0
	v_mov_b32_e32 v126, v0
	v_mov_b32_e32 v127, v0
	v_mov_b32_e32 v64, v0
	v_mov_b32_e32 v65, v0
	v_mov_b32_e32 v66, v0
	v_mov_b32_e32 v67, v0
	v_mov_b32_e32 v72, v0
	v_mov_b32_e32 v73, v0
	v_mov_b32_e32 v74, v0
	v_mov_b32_e32 v75, v0
	v_mov_b32_e32 v80, v0
	v_mov_b32_e32 v81, v0
	v_mov_b32_e32 v82, v0
	v_mov_b32_e32 v83, v0
	v_mov_b32_e32 v88, v0
	v_mov_b32_e32 v89, v0
	v_mov_b32_e32 v90, v0
	v_mov_b32_e32 v91, v0
	v_mov_b32_e32 v96, v0
	v_mov_b32_e32 v97, v0
	v_mov_b32_e32 v98, v0
	v_mov_b32_e32 v99, v0
	v_mov_b32_e32 v104, v0
	v_mov_b32_e32 v105, v0
	v_mov_b32_e32 v106, v0
	v_mov_b32_e32 v107, v0
	v_mov_b32_e32 v112, v0
	v_mov_b32_e32 v113, v0
	v_mov_b32_e32 v114, v0
	v_mov_b32_e32 v115, v0
	v_mov_b32_e32 v120, v0
	v_mov_b32_e32 v121, v0
	v_mov_b32_e32 v122, v0
	v_mov_b32_e32 v123, v0

; __device__ __forceinline__ unsigned cvt_pk_bf16(float lo, float hi) { unsigned r; asm volatile("v_cvt_pk_bf16_f32 %0, %1, %2" : "=v"(r) : "v"(lo), "v"(hi)); return r; }
;     __device__ __forceinline__ void operator()(const f32x4 (&acc)[2][2][4][2], const Unit& u, int wr, int wc, int fr, int fq) const {
;         const int col = u.pn * 128 + wc * 32 + 8 * fq; const int row0 = u.pm * 256 + wr * 64 + fr;
;         float rsv[8];
; #pragma unroll
;         for (int i = 0; i < 8; ++i) rsv[i] = ssq[row0 + (i >> 2) * 128 + (i & 3) * 16];
; #pragma unroll
;         for (int ai = 0; ai < 2; ++ai)
; #pragma unroll
;             for (int m = 0; m < 4; ++m) { const int row = row0 + ai * 128 + m * 16; const float rs = rsqrtf(rsv[ai * 4 + m] * (1.f / D) + EPS); float h[8];
; #pragma unroll
;                 for (int j = 0; j < 8; ++j) { const float gv = acc[ai][0][m][j >> 2][j & 3] * rs, uv = acc[ai][1][m][j >> 2][j & 3] * rs; h[j] = gv / (1.f + __expf(-gv)) * uv; }
;                 u32x4 w; w.x = cvt_pk_bf16(h[0], h[1]); w.y = cvt_pk_bf16(h[2], h[3]); w.z = cvt_pk_bf16(h[4], h[5]); w.w = cvt_pk_bf16(h[6], h[7]);
;                 *(u32x4*)(H + (size_t)row * FF + col) = w; }
.LBB0_1604:
	s_lshl_b32 s100, s8, 8
	s_mul_i32 s101, s100, 0x1600
	s_lshl_b32 s100, s9, 8
	s_add_i32 s101, s101, s100
	s_add_u32 s98, s96, s101
	s_addc_u32 s99, s97, 0
	v_lshlrev_b32_e32 v250, 1, v151
	v_mad_u32_u24 v250, v131, s52, v250
	s_and_b64 s[100:101], s[6:7], exec
	s_cselect_b32 s100, s8, s28
	v_lshl_add_u32 v253, s100, 8, v131
	v_lshlrev_b32_e32 v253, 2, v253
	v_fmamk_f32 v252, v242, 0x3a800000, v155
	v_rsq_f32_e32 v251, v252
	global_load_dword v242, v253, s[14:15] offset:0
	v_mul_f32_e32 v124, v120, v124
	v_mul_f32_e32 v125, v121, v125
	v_mul_f32_e32 v126, v122, v126
	v_mul_f32_e32 v127, v123, v127
	v_mul_f32_e32 v116, v112, v116
	v_mul_f32_e32 v117, v113, v117
	v_mul_f32_e32 v118, v114, v118
	v_mul_f32_e32 v119, v115, v119
	v_mul_f32_e32 v251, 0xbfb8aa3b, v251
	v_mul_f32_e32 v120, v251, v120
	v_mul_f32_e32 v121, v251, v121
	v_mul_f32_e32 v122, v251, v122
	v_mul_f32_e32 v123, v251, v123
	v_mul_f32_e32 v112, v251, v112
	v_mul_f32_e32 v113, v251, v113
	v_mul_f32_e32 v114, v251, v114
	v_mul_f32_e32 v115, v251, v115
	v_exp_f32_e32 v120, v120
	v_exp_f32_e32 v121, v121
	v_exp_f32_e32 v122, v122
	v_exp_f32_e32 v123, v123
	v_exp_f32_e32 v112, v112
	v_exp_f32_e32 v113, v113
	v_exp_f32_e32 v114, v114
	v_exp_f32_e32 v115, v115
	v_fma_f32 v120, v120, v252, v252
	v_fma_f32 v121, v121, v252, v252
	v_fma_f32 v122, v122, v252, v252
	v_fma_f32 v123, v123, v252, v252
	v_fma_f32 v112, v112, v252, v252
	v_fma_f32 v113, v113, v252, v252
	v_fma_f32 v114, v114, v252, v252
	v_fma_f32 v115, v115, v252, v252
	v_rcp_f32_e32 v120, v120
	v_rcp_f32_e32 v121, v121
	v_rcp_f32_e32 v122, v122
	v_rcp_f32_e32 v123, v123
	v_rcp_f32_e32 v112, v112
	v_rcp_f32_e32 v113, v113
	v_rcp_f32_e32 v114, v114
	v_rcp_f32_e32 v115, v115
	v_mul_f32_e32 v124, v124, v120
	v_mul_f32_e32 v125, v125, v121
	v_mul_f32_e32 v126, v126, v122
	v_mul_f32_e32 v127, v127, v123
	v_mul_f32_e32 v116, v116, v112
	v_mul_f32_e32 v117, v117, v113
	v_mul_f32_e32 v118, v118, v114
	v_mul_f32_e32 v119, v119, v115
	v_cvt_pk_bf16_f32 v120, v124, v125
	v_cvt_pk_bf16_f32 v121, v126, v127
	v_cvt_pk_bf16_f32 v122, v116, v117
	v_cvt_pk_bf16_f32 v123, v118, v119
	global_store_dwordx4 v250, v[120:123], s[98:99]
	v_fmamk_f32 v252, v243, 0x3a800000, v155
	v_rsq_f32_e32 v251, v252
	global_load_dword v243, v253, s[14:15] offset:64
	v_mul_f32_e32 v108, v104, v108
	v_mul_f32_e32 v109, v105, v109
	v_mul_f32_e32 v110, v106, v110
	v_mul_f32_e32 v111, v107, v111
	v_mul_f32_e32 v100, v96, v100
	v_mul_f32_e32 v101, v97, v101
	v_mul_f32_e32 v102, v98, v102
	v_mul_f32_e32 v103, v99, v103
	v_mul_f32_e32 v251, 0xbfb8aa3b, v251
	v_mul_f32_e32 v104, v251, v104
	v_mul_f32_e32 v105, v251, v105
	v_mul_f32_e32 v106, v251, v106
	v_mul_f32_e32 v107, v251, v107
	v_mul_f32_e32 v96, v251, v96
	v_mul_f32_e32 v97, v251, v97
	v_mul_f32_e32 v98, v251, v98
	v_mul_f32_e32 v99, v251, v99
	v_exp_f32_e32 v104, v104
	v_exp_f32_e32 v105, v105
	v_exp_f32_e32 v106, v106
	v_exp_f32_e32 v107, v107
	v_exp_f32_e32 v96, v96
	v_exp_f32_e32 v97, v97
	v_exp_f32_e32 v98, v98
	v_exp_f32_e32 v99, v99
	v_fma_f32 v104, v104, v252, v252
	v_fma_f32 v105, v105, v252, v252
	v_fma_f32 v106, v106, v252, v252
	v_fma_f32 v107, v107, v252, v252
	v_fma_f32 v96, v96, v252, v252
	v_fma_f32 v97, v97, v252, v252
	v_fma_f32 v98, v98, v252, v252
	v_fma_f32 v99, v99, v252, v252
	v_rcp_f32_e32 v104, v104
	v_rcp_f32_e32 v105, v105
	v_rcp_f32_e32 v106, v106
	v_rcp_f32_e32 v107, v107
	v_rcp_f32_e32 v96, v96
	v_rcp_f32_e32 v97, v97
	v_rcp_f32_e32 v98, v98
	v_rcp_f32_e32 v99, v99
	v_mul_f32_e32 v108, v108, v104
	v_mul_f32_e32 v109, v109, v105
	v_mul_f32_e32 v110, v110, v106
	v_mul_f32_e32 v111, v111, v107
	v_mul_f32_e32 v100, v100, v96
	v_mul_f32_e32 v101, v101, v97
	v_mul_f32_e32 v102, v102, v98
	v_mul_f32_e32 v103, v103, v99
	v_cvt_pk_bf16_f32 v104, v108, v109
	v_cvt_pk_bf16_f32 v105, v110, v111
	v_cvt_pk_bf16_f32 v106, v100, v101
	v_cvt_pk_bf16_f32 v107, v102, v103
	s_add_u32 s98, s98, 0x16000
	s_addc_u32 s99, s99, 0
	global_store_dwordx4 v250, v[104:107], s[98:99]
	v_fmamk_f32 v252, v244, 0x3a800000, v155
	v_rsq_f32_e32 v251, v252
	global_load_dword v244, v253, s[14:15] offset:128
	v_mul_f32_e32 v92, v88, v92
	v_mul_f32_e32 v93, v89, v93
	v_mul_f32_e32 v94, v90, v94
	v_mul_f32_e32 v95, v91, v95
	v_mul_f32_e32 v84, v80, v84
	v_mul_f32_e32 v85, v81, v85
	v_mul_f32_e32 v86, v82, v86
	v_mul_f32_e32 v87, v83, v87
	v_mul_f32_e32 v251, 0xbfb8aa3b, v251
	v_mul_f32_e32 v88, v251, v88
	v_mul_f32_e32 v89, v251, v89
	v_mul_f32_e32 v90, v251, v90
	v_mul_f32_e32 v91, v251, v91
	v_mul_f32_e32 v80, v251, v80
	v_mul_f32_e32 v81, v251, v81
	v_mul_f32_e32 v82, v251, v82
	v_mul_f32_e32 v83, v251, v83
	v_exp_f32_e32 v88, v88
	v_exp_f32_e32 v89, v89
	v_exp_f32_e32 v90, v90
	v_exp_f32_e32 v91, v91
	v_exp_f32_e32 v80, v80
	v_exp_f32_e32 v81, v81
	v_exp_f32_e32 v82, v82
	v_exp_f32_e32 v83, v83
	v_fma_f32 v88, v88, v252, v252
	v_fma_f32 v89, v89, v252, v252
	v_fma_f32 v90, v90, v252, v252
	v_fma_f32 v91, v91, v252, v252
	v_fma_f32 v80, v80, v252, v252
	v_fma_f32 v81, v81, v252, v252
	v_fma_f32 v82, v82, v252, v252
	v_fma_f32 v83, v83, v252, v252
	v_rcp_f32_e32 v88, v88
	v_rcp_f32_e32 v89, v89
	v_rcp_f32_e32 v90, v90
	v_rcp_f32_e32 v91, v91
	v_rcp_f32_e32 v80, v80
	v_rcp_f32_e32 v81, v81
	v_rcp_f32_e32 v82, v82
	v_rcp_f32_e32 v83, v83
	v_mul_f32_e32 v92, v92, v88
	v_mul_f32_e32 v93, v93, v89
	v_mul_f32_e32 v94, v94, v90
	v_mul_f32_e32 v95, v95, v91
	v_mul_f32_e32 v84, v84, v80
	v_mul_f32_e32 v85, v85, v81
	v_mul_f32_e32 v86, v86, v82
	v_mul_f32_e32 v87, v87, v83
	v_cvt_pk_bf16_f32 v88, v92, v93
	v_cvt_pk_bf16_f32 v89, v94, v95
	v_cvt_pk_bf16_f32 v90, v84, v85
	v_cvt_pk_bf16_f32 v91, v86, v87
; __device__ __forceinline__ unsigned cvt_pk_bf16(float lo, float hi) { unsigned r; asm volatile("v_cvt_pk_bf16_f32 %0, %1, %2" : "=v"(r) : "v"(lo), "v"(hi)); return r; }
;     __device__ __forceinline__ void operator()(const f32x4 (&acc)[2][2][4][2], const Unit& u, int wr, int wc, int fr, int fq) const {
;     ...
;             for (int m = 0; m < 4; ++m) { const int row = row0 + ai * 128 + m * 16; const float rs = rsqrtf(rsv[ai * 4 + m] * (1.f / D) + EPS); float h[8];
; #pragma unroll
;                 for (int j = 0; j < 8; ++j) { const float gv = acc[ai][0][m][j >> 2][j & 3] * rs, uv = acc[ai][1][m][j >> 2][j & 3] * rs; h[j] = gv / (1.f + __expf(-gv)) * uv; }
;                 u32x4 w; w.x = cvt_pk_bf16(h[0], h[1]); w.y = cvt_pk_bf16(h[2], h[3]); w.z = cvt_pk_bf16(h[4], h[5]); w.w = cvt_pk_bf16(h[6], h[7]);
;                 *(u32x4*)(H + (size_t)row * FF + col) = w; }
	s_add_u32 s98, s98, 0x16000
	s_addc_u32 s99, s99, 0
	global_store_dwordx4 v250, v[88:91], s[98:99]
	v_fmamk_f32 v252, v245, 0x3a800000, v155
	v_rsq_f32_e32 v251, v252
	global_load_dword v245, v253, s[14:15] offset:192
	v_mul_f32_e32 v76, v72, v76
	v_mul_f32_e32 v77, v73, v77
	v_mul_f32_e32 v78, v74, v78
	v_mul_f32_e32 v79, v75, v79
	v_mul_f32_e32 v68, v64, v68
	v_mul_f32_e32 v69, v65, v69
	v_mul_f32_e32 v70, v66, v70
	v_mul_f32_e32 v71, v67, v71
	v_mul_f32_e32 v251, 0xbfb8aa3b, v251
	v_mul_f32_e32 v72, v251, v72
	v_mul_f32_e32 v73, v251, v73
	v_mul_f32_e32 v74, v251, v74
	v_mul_f32_e32 v75, v251, v75
	v_mul_f32_e32 v64, v251, v64
	v_mul_f32_e32 v65, v251, v65
	v_mul_f32_e32 v66, v251, v66
	v_mul_f32_e32 v67, v251, v67
	v_exp_f32_e32 v72, v72
	v_exp_f32_e32 v73, v73
	v_exp_f32_e32 v74, v74
	v_exp_f32_e32 v75, v75
	v_exp_f32_e32 v64, v64
	v_exp_f32_e32 v65, v65
	v_exp_f32_e32 v66, v66
	v_exp_f32_e32 v67, v67
	v_fma_f32 v72, v72, v252, v252
	v_fma_f32 v73, v73, v252, v252
	v_fma_f32 v74, v74, v252, v252
	v_fma_f32 v75, v75, v252, v252
	v_fma_f32 v64, v64, v252, v252
	v_fma_f32 v65, v65, v252, v252
	v_fma_f32 v66, v66, v252, v252
	v_fma_f32 v67, v67, v252, v252
	v_rcp_f32_e32 v72, v72
	v_rcp_f32_e32 v73, v73
	v_rcp_f32_e32 v74, v74
	v_rcp_f32_e32 v75, v75
	v_rcp_f32_e32 v64, v64
	v_rcp_f32_e32 v65, v65
	v_rcp_f32_e32 v66, v66
	v_rcp_f32_e32 v67, v67
	v_mul_f32_e32 v76, v76, v72
	v_mul_f32_e32 v77, v77, v73
	v_mul_f32_e32 v78, v78, v74
	v_mul_f32_e32 v79, v79, v75
	v_mul_f32_e32 v68, v68, v64
	v_mul_f32_e32 v69, v69, v65
	v_mul_f32_e32 v70, v70, v66
	v_mul_f32_e32 v71, v71, v67
	v_cvt_pk_bf16_f32 v72, v76, v77
	v_cvt_pk_bf16_f32 v73, v78, v79
	v_cvt_pk_bf16_f32 v74, v68, v69
	v_cvt_pk_bf16_f32 v75, v70, v71
	s_add_u32 s98, s98, 0x16000
	s_addc_u32 s99, s99, 0
	global_store_dwordx4 v250, v[72:75], s[98:99]
	v_fmamk_f32 v252, v246, 0x3a800000, v155
	v_rsq_f32_e32 v251, v252
	global_load_dword v246, v253, s[14:15] offset:512
	v_mul_f32_e32 v60, v56, v60
	v_mul_f32_e32 v61, v57, v61
	v_mul_f32_e32 v62, v58, v62
	v_mul_f32_e32 v63, v59, v63
	v_mul_f32_e32 v52, v48, v52
	v_mul_f32_e32 v53, v49, v53
	v_mul_f32_e32 v54, v50, v54
	v_mul_f32_e32 v55, v51, v55
	v_mul_f32_e32 v251, 0xbfb8aa3b, v251
	v_mul_f32_e32 v56, v251, v56
	v_mul_f32_e32 v57, v251, v57
	v_mul_f32_e32 v58, v251, v58
	v_mul_f32_e32 v59, v251, v59
	v_mul_f32_e32 v48, v251, v48
	v_mul_f32_e32 v49, v251, v49
	v_mul_f32_e32 v50, v251, v50
	v_mul_f32_e32 v51, v251, v51
	v_exp_f32_e32 v56, v56
	v_exp_f32_e32 v57, v57
	v_exp_f32_e32 v58, v58
	v_exp_f32_e32 v59, v59
	v_exp_f32_e32 v48, v48
	v_exp_f32_e32 v49, v49
	v_exp_f32_e32 v50, v50
	v_exp_f32_e32 v51, v51
	v_fma_f32 v56, v56, v252, v252
	v_fma_f32 v57, v57, v252, v252
	v_fma_f32 v58, v58, v252, v252
	v_fma_f32 v59, v59, v252, v252
	v_fma_f32 v48, v48, v252, v252
	v_fma_f32 v49, v49, v252, v252
	v_fma_f32 v50, v50, v252, v252
	v_fma_f32 v51, v51, v252, v252
	v_rcp_f32_e32 v56, v56
	v_rcp_f32_e32 v57, v57
	v_rcp_f32_e32 v58, v58
	v_rcp_f32_e32 v59, v59
	v_rcp_f32_e32 v48, v48
	v_rcp_f32_e32 v49, v49
	v_rcp_f32_e32 v50, v50
	v_rcp_f32_e32 v51, v51
	v_mul_f32_e32 v60, v60, v56
	v_mul_f32_e32 v61, v61, v57
	v_mul_f32_e32 v62, v62, v58
	v_mul_f32_e32 v63, v63, v59
	v_mul_f32_e32 v52, v52, v48
	v_mul_f32_e32 v53, v53, v49
	v_mul_f32_e32 v54, v54, v50
	v_mul_f32_e32 v55, v55, v51
	v_cvt_pk_bf16_f32 v56, v60, v61
	v_cvt_pk_bf16_f32 v57, v62, v63
	v_cvt_pk_bf16_f32 v58, v52, v53
	v_cvt_pk_bf16_f32 v59, v54, v55
	s_add_u32 s98, s98, 0x6e000
	s_addc_u32 s99, s99, 0
	global_store_dwordx4 v250, v[56:59], s[98:99]
	v_fmamk_f32 v252, v247, 0x3a800000, v155
	v_rsq_f32_e32 v251, v252
	global_load_dword v247, v253, s[14:15] offset:576
	v_mul_f32_e32 v44, v40, v44
	v_mul_f32_e32 v45, v41, v45
	v_mul_f32_e32 v46, v42, v46
	v_mul_f32_e32 v47, v43, v47
	v_mul_f32_e32 v36, v32, v36
	v_mul_f32_e32 v37, v33, v37
	v_mul_f32_e32 v38, v34, v38
	v_mul_f32_e32 v39, v35, v39
	v_mul_f32_e32 v251, 0xbfb8aa3b, v251
	v_mul_f32_e32 v40, v251, v40
	v_mul_f32_e32 v41, v251, v41
	v_mul_f32_e32 v42, v251, v42
	v_mul_f32_e32 v43, v251, v43
	v_mul_f32_e32 v32, v251, v32
	v_mul_f32_e32 v33, v251, v33
	v_mul_f32_e32 v34, v251, v34
	v_mul_f32_e32 v35, v251, v35
	v_exp_f32_e32 v40, v40
	v_exp_f32_e32 v41, v41
	v_exp_f32_e32 v42, v42
	v_exp_f32_e32 v43, v43
	v_exp_f32_e32 v32, v32
	v_exp_f32_e32 v33, v33
	v_exp_f32_e32 v34, v34
	v_exp_f32_e32 v35, v35
	v_fma_f32 v40, v40, v252, v252
; __device__ __forceinline__ unsigned cvt_pk_bf16(float lo, float hi) { unsigned r; asm volatile("v_cvt_pk_bf16_f32 %0, %1, %2" : "=v"(r) : "v"(lo), "v"(hi)); return r; }
; #define PG8_BAR __builtin_amdgcn_s_barrier()
;     __device__ __forceinline__ void init(f32x4 (&acc)[2][2][4][2], const Unit&, int, int, int, int) const { acc_zero(acc); }
;     __device__ __forceinline__ void init(f32x4 (&acc)[2][2][4][2], const Unit&, int, int, int, int) const { acc_zero(acc); }
;     __device__ __forceinline__ void init(f32x4 (&acc)[2][2][4][2], const Unit&, int, int, int, int) const { acc_zero(acc); }
; template <class Epi, class Sched>
; __device__ __forceinline__ void gemm_phase(PG8_LAS unsigned char* lds, const Gemm g, const Sched& S, const Epi& E) {
;     ...
;         if (!has_next) break;
;         E.init(acc, nxt, wr, wc, fr, fq);
;         cur = nxt; cA = nA; cB = nB; ++ui;
;         if (wr == 1) PG8_BAR;
;     __device__ __forceinline__ void operator()(const f32x4 (&acc)[2][2][4][2], const Unit& u, int wr, int wc, int fr, int fq) const {
;     ...
;             for (int m = 0; m < 4; ++m) { const int row = row0 + ai * 128 + m * 16; const float rs = rsqrtf(rsv[ai * 4 + m] * (1.f / D) + EPS); float h[8];
; #pragma unroll
;                 for (int j = 0; j < 8; ++j) { const float gv = acc[ai][0][m][j >> 2][j & 3] * rs, uv = acc[ai][1][m][j >> 2][j & 3] * rs; h[j] = gv / (1.f + __expf(-gv)) * uv; }
;                 u32x4 w; w.x = cvt_pk_bf16(h[0], h[1]); w.y = cvt_pk_bf16(h[2], h[3]); w.z = cvt_pk_bf16(h[4], h[5]); w.w = cvt_pk_bf16(h[6], h[7]);
;                 *(u32x4*)(H + (size_t)row * FF + col) = w; }
	v_fma_f32 v41, v41, v252, v252
	v_fma_f32 v42, v42, v252, v252
	v_fma_f32 v43, v43, v252, v252
	v_fma_f32 v32, v32, v252, v252
	v_fma_f32 v33, v33, v252, v252
	v_fma_f32 v34, v34, v252, v252
	v_fma_f32 v35, v35, v252, v252
	v_rcp_f32_e32 v40, v40
	v_rcp_f32_e32 v41, v41
	v_rcp_f32_e32 v42, v42
	v_rcp_f32_e32 v43, v43
	v_rcp_f32_e32 v32, v32
	v_rcp_f32_e32 v33, v33
	v_rcp_f32_e32 v34, v34
	v_rcp_f32_e32 v35, v35
	v_mul_f32_e32 v44, v44, v40
	v_mul_f32_e32 v45, v45, v41
	v_mul_f32_e32 v46, v46, v42
	v_mul_f32_e32 v47, v47, v43
	v_mul_f32_e32 v36, v36, v32
	v_mul_f32_e32 v37, v37, v33
	v_mul_f32_e32 v38, v38, v34
	v_mul_f32_e32 v39, v39, v35
	v_cvt_pk_bf16_f32 v40, v44, v45
	v_cvt_pk_bf16_f32 v41, v46, v47
	v_cvt_pk_bf16_f32 v42, v36, v37
	v_cvt_pk_bf16_f32 v43, v38, v39
	s_add_u32 s98, s98, 0x16000
	s_addc_u32 s99, s99, 0
	global_store_dwordx4 v250, v[40:43], s[98:99]
	v_fmamk_f32 v252, v248, 0x3a800000, v155
	v_rsq_f32_e32 v251, v252
	global_load_dword v248, v253, s[14:15] offset:640
	v_mul_f32_e32 v28, v24, v28
	v_mul_f32_e32 v29, v25, v29
	v_mul_f32_e32 v30, v26, v30
	v_mul_f32_e32 v31, v27, v31
	v_mul_f32_e32 v20, v16, v20
	v_mul_f32_e32 v21, v17, v21
	v_mul_f32_e32 v22, v18, v22
	v_mul_f32_e32 v23, v19, v23
	v_mul_f32_e32 v251, 0xbfb8aa3b, v251
	v_mul_f32_e32 v24, v251, v24
	v_mul_f32_e32 v25, v251, v25
	v_mul_f32_e32 v26, v251, v26
	v_mul_f32_e32 v27, v251, v27
	v_mul_f32_e32 v16, v251, v16
	v_mul_f32_e32 v17, v251, v17
	v_mul_f32_e32 v18, v251, v18
	v_mul_f32_e32 v19, v251, v19
	v_exp_f32_e32 v24, v24
	v_exp_f32_e32 v25, v25
	v_exp_f32_e32 v26, v26
	v_exp_f32_e32 v27, v27
	v_exp_f32_e32 v16, v16
	v_exp_f32_e32 v17, v17
	v_exp_f32_e32 v18, v18
	v_exp_f32_e32 v19, v19
	v_fma_f32 v24, v24, v252, v252
	v_fma_f32 v25, v25, v252, v252
	v_fma_f32 v26, v26, v252, v252
	v_fma_f32 v27, v27, v252, v252
	v_fma_f32 v16, v16, v252, v252
	v_fma_f32 v17, v17, v252, v252
	v_fma_f32 v18, v18, v252, v252
	v_fma_f32 v19, v19, v252, v252
	v_rcp_f32_e32 v24, v24
	v_rcp_f32_e32 v25, v25
	v_rcp_f32_e32 v26, v26
	v_rcp_f32_e32 v27, v27
	v_rcp_f32_e32 v16, v16
	v_rcp_f32_e32 v17, v17
	v_rcp_f32_e32 v18, v18
	v_rcp_f32_e32 v19, v19
	v_mul_f32_e32 v28, v28, v24
	v_mul_f32_e32 v29, v29, v25
	v_mul_f32_e32 v30, v30, v26
	v_mul_f32_e32 v31, v31, v27
	v_mul_f32_e32 v20, v20, v16
	v_mul_f32_e32 v21, v21, v17
	v_mul_f32_e32 v22, v22, v18
	v_mul_f32_e32 v23, v23, v19
	v_cvt_pk_bf16_f32 v24, v28, v29
	v_cvt_pk_bf16_f32 v25, v30, v31
	v_cvt_pk_bf16_f32 v26, v20, v21
	v_cvt_pk_bf16_f32 v27, v22, v23
	s_add_u32 s98, s98, 0x16000
	s_addc_u32 s99, s99, 0
	global_store_dwordx4 v250, v[24:27], s[98:99]
	v_fmamk_f32 v252, v249, 0x3a800000, v155
	v_rsq_f32_e32 v251, v252
	global_load_dword v249, v253, s[14:15] offset:704
	v_mul_f32_e32 v12, v8, v12
	v_mul_f32_e32 v13, v9, v13
	v_mul_f32_e32 v14, v10, v14
	v_mul_f32_e32 v15, v11, v15
	v_mul_f32_e32 v0, v4, v0
	v_mul_f32_e32 v1, v5, v1
	v_mul_f32_e32 v2, v6, v2
	v_mul_f32_e32 v3, v7, v3
	v_mul_f32_e32 v251, 0xbfb8aa3b, v251
	v_mul_f32_e32 v8, v251, v8
	v_mul_f32_e32 v9, v251, v9
	v_mul_f32_e32 v10, v251, v10
	v_mul_f32_e32 v11, v251, v11
	v_mul_f32_e32 v4, v251, v4
	v_mul_f32_e32 v5, v251, v5
	v_mul_f32_e32 v6, v251, v6
	v_mul_f32_e32 v7, v251, v7
	v_exp_f32_e32 v8, v8
	v_exp_f32_e32 v9, v9
	v_exp_f32_e32 v10, v10
	v_exp_f32_e32 v11, v11
	v_exp_f32_e32 v4, v4
	v_exp_f32_e32 v5, v5
	v_exp_f32_e32 v6, v6
	v_exp_f32_e32 v7, v7
	v_fma_f32 v8, v8, v252, v252
	v_fma_f32 v9, v9, v252, v252
	v_fma_f32 v10, v10, v252, v252
	v_fma_f32 v11, v11, v252, v252
	v_fma_f32 v4, v4, v252, v252
	v_fma_f32 v5, v5, v252, v252
	v_fma_f32 v6, v6, v252, v252
	v_fma_f32 v7, v7, v252, v252
	v_rcp_f32_e32 v8, v8
	v_rcp_f32_e32 v9, v9
	v_rcp_f32_e32 v10, v10
	v_rcp_f32_e32 v11, v11
	v_rcp_f32_e32 v4, v4
	v_rcp_f32_e32 v5, v5
	v_rcp_f32_e32 v6, v6
	v_rcp_f32_e32 v7, v7
	v_mul_f32_e32 v12, v12, v8
	v_mul_f32_e32 v13, v13, v9
	v_mul_f32_e32 v14, v14, v10
	v_mul_f32_e32 v15, v15, v11
	v_mul_f32_e32 v0, v0, v4
	v_mul_f32_e32 v1, v1, v5
	v_mul_f32_e32 v2, v2, v6
	v_mul_f32_e32 v3, v3, v7
	v_cvt_pk_bf16_f32 v8, v12, v13
	v_cvt_pk_bf16_f32 v9, v14, v15
	v_cvt_pk_bf16_f32 v10, v0, v1
	v_cvt_pk_bf16_f32 v11, v2, v3
	s_add_u32 s98, s98, 0x16000
	s_addc_u32 s99, s99, 0
	global_store_dwordx4 v250, v[8:11], s[98:99]
	s_and_b64 vcc, exec, s[6:7]
	s_mov_b64 s[0:1], -1
	s_cbranch_vccnz .LBB0_1594
	s_andn2_b64 vcc, exec, s[20:21]
	s_cbranch_vccnz .LBB0_1593
	s_barrier
	s_branch .LBB0_1593

; __global__ void __launch_bounds__(512, 2) fwd_kernel(Args a) {
	.amdhsa_kernel _Z10fwd_kernel4Args
		.amdhsa_group_segment_fixed_size 0
		.amdhsa_private_segment_fixed_size 0
		.amdhsa_kernarg_size 464
		.amdhsa_user_sgpr_count 2
		.amdhsa_user_sgpr_dispatch_ptr 0
		.amdhsa_user_sgpr_queue_ptr 0
		.amdhsa_user_sgpr_kernarg_segment_ptr 1
		.amdhsa_user_sgpr_dispatch_id 0
		.amdhsa_user_sgpr_kernarg_preload_length 0
		.amdhsa_user_sgpr_kernarg_preload_offset 0
		.amdhsa_user_sgpr_private_segment_size 0
		.amdhsa_uses_dynamic_stack 0
		.amdhsa_enable_private_segment 0
		.amdhsa_system_sgpr_workgroup_id_x 1
		.amdhsa_system_sgpr_workgroup_id_y 0
		.amdhsa_system_sgpr_workgroup_id_z 0
		.amdhsa_system_sgpr_workgroup_info 0
		.amdhsa_system_vgpr_workitem_id 2
		.amdhsa_next_free_vgpr 254
		.amdhsa_next_free_sgpr 102
		.amdhsa_accum_offset 256
		.amdhsa_reserve_vcc 1
		.amdhsa_float_round_mode_32 0
		.amdhsa_float_round_mode_16_64 0
		.amdhsa_float_denorm_mode_32 3
		.amdhsa_float_denorm_mode_16_64 3
		.amdhsa_dx10_clamp 1
		.amdhsa_ieee_mode 1
		.amdhsa_fp16_overflow 0
		.amdhsa_tg_split 0
		.amdhsa_exception_fp_ieee_invalid_op 0
		.amdhsa_exception_fp_denorm_src 0
		.amdhsa_exception_fp_ieee_div_zero 0
		.amdhsa_exception_fp_ieee_overflow 0
		.amdhsa_exception_fp_ieee_underflow 0
		.amdhsa_exception_fp_ieee_inexact 0
		.amdhsa_exception_int_div_zero 0
	.end_amdhsa_kernel

; __global__ void __launch_bounds__(512, 2) fwd_kernel(Args a) {
amdhsa.kernels:
  - .agpr_count:     0
    .args:
      - .offset:         0
        .size:           208
        .value_kind:     by_value
      - .offset:         208
        .size:           4
        .value_kind:     hidden_block_count_x
      - .offset:         212
        .size:           4
        .value_kind:     hidden_block_count_y
      - .offset:         216
        .size:           4
        .value_kind:     hidden_block_count_z
      - .offset:         220
        .size:           2
        .value_kind:     hidden_group_size_x
      - .offset:         222
        .size:           2
        .value_kind:     hidden_group_size_y
      - .offset:         224
        .size:           2
        .value_kind:     hidden_group_size_z
      - .offset:         226
        .size:           2
        .value_kind:     hidden_remainder_x
      - .offset:         228
        .size:           2
        .value_kind:     hidden_remainder_y
      - .offset:         230
        .size:           2
        .value_kind:     hidden_remainder_z
      - .offset:         248
        .size:           8
        .value_kind:     hidden_global_offset_x
      - .offset:         256
        .size:           8
        .value_kind:     hidden_global_offset_y
      - .offset:         264
        .size:           8
        .value_kind:     hidden_global_offset_z
      - .offset:         272
        .size:           2
        .value_kind:     hidden_grid_dims
      - .offset:         296
        .size:           8
        .value_kind:     hidden_multigrid_sync_arg
      - .offset:         328
        .size:           4
        .value_kind:     hidden_dynamic_lds_size
    .group_segment_fixed_size: 0
    .kernarg_segment_align: 8
    .kernarg_segment_size: 464
    .language:       OpenCL C
    .language_version:
      - 2
      - 0
    .max_flat_workgroup_size: 512
    .name:           _Z10fwd_kernel4Args
    .private_segment_fixed_size: 0
    .sgpr_count:     108
    .sgpr_spill_count: 57
    .symbol:         _Z10fwd_kernel4Args.kd
    .uniform_work_group_size: 1
    .uses_dynamic_stack: false
    .vgpr_count:     254
    .vgpr_spill_count: 0
    .wavefront_size: 64
